# MIX stores sc1 (write-through)
# baseline (speedup 1.0000x reference)
.LBB0_314:
	s_or_b64 exec, exec, s[40:41]
	v_or_b32_e32 v187, s11, v233
	v_lshlrev_b32_e32 v187, 11, v187
	v_lshl_add_u32 v187, v210, 1, v187
	v_mov_b32_e32 v250, 0
	v_mov_b32_e32 v251, 0
	v_mov_b32_e32 v252, 0
	v_mov_b32_e32 v253, 0
	s_mov_b64 s[40:41], exec
	s_and_b64 exec, exec, s[8:9]
	v_add_u32_e32 v187, 0x38000, v187
	s_nop 0
	global_load_dwordx4 v[250:253], v187, s[50:51]
	v_add_u32_e32 v187, 0xfffc8000, v187
	s_mov_b64 exec, s[40:41]
	global_load_dwordx4 v[188:191], v187, s[50:51]
	v_add_u32_e32 v187, 0x8000, v187
	global_load_dwordx4 v[192:195], v187, s[50:51]
	v_add_u32_e32 v187, 0x8000, v187
	global_load_dwordx4 v[196:199], v187, s[50:51]
	v_add_u32_e32 v187, 0x8000, v187
	global_load_dwordx4 v[228:231], v187, s[50:51]
	v_add_u32_e32 v187, 0x28000, v187
	global_load_dwordx4 v[246:249], v187, s[50:51]
	v_mul_f32_e32 v144, 0xbfb8aa3b, v128
	v_mul_f32_e32 v145, 0xbfb8aa3b, v129
	v_exp_f32_e32 v144, v144
	v_exp_f32_e32 v145, v145
	v_mul_f32_e32 v146, 0xbfb8aa3b, v130
	v_mul_f32_e32 v147, 0xbfb8aa3b, v131
	v_exp_f32_e32 v146, v146
	v_exp_f32_e32 v147, v147
	v_add_f32_e32 v144, 1.0, v144
	v_add_f32_e32 v145, 1.0, v145
	v_rcp_f32_e32 v144, v144
	v_rcp_f32_e32 v145, v145
	v_add_f32_e32 v146, 1.0, v146
	v_add_f32_e32 v147, 1.0, v147
	v_rcp_f32_e32 v146, v146
	v_rcp_f32_e32 v147, v147
	v_pk_mul_f32 v[164:165], v[128:129], v[144:145]
	v_mul_f32_e32 v144, 0xbfb8aa3b, v120
	v_mul_f32_e32 v145, 0xbfb8aa3b, v121
	v_exp_f32_e32 v144, v144
	v_exp_f32_e32 v145, v145
	v_pk_mul_f32 v[166:167], v[130:131], v[146:147]
	v_mul_f32_e32 v146, 0xbfb8aa3b, v122
	v_mul_f32_e32 v147, 0xbfb8aa3b, v123
	v_exp_f32_e32 v146, v146
	v_exp_f32_e32 v147, v147
	v_add_f32_e32 v144, 1.0, v144
	v_add_f32_e32 v145, 1.0, v145
	v_rcp_f32_e32 v144, v144
	v_rcp_f32_e32 v145, v145
	v_or_b32_e32 v162, s11, v233
	v_add_f32_e32 v146, 1.0, v146
	v_add_f32_e32 v147, 1.0, v147
	v_rcp_f32_e32 v146, v146
	v_rcp_f32_e32 v147, v147
	v_ashrrev_i32_e32 v163, 31, v162
	v_pk_mul_f32 v[170:171], v[120:121], v[144:145]
	v_lshlrev_b64 v[144:145], 11, v[162:163]
	v_lshl_add_u64 v[144:145], s[50:51], 0, v[144:145]
	v_lshlrev_b64 v[160:161], 1, v[210:211]
	v_lshl_add_u64 v[144:145], v[144:145], 0, v[160:161]
	v_pk_mul_f32 v[168:169], v[122:123], v[146:147]
	s_waitcnt vmcnt(4)
	v_mov_b32_e32 v144, v188
	v_mov_b32_e32 v145, v189
	v_mov_b32_e32 v146, v190
	v_mov_b32_e32 v147, v191
	v_add_u32_e32 v187, 0x8000, v187
	global_load_dwordx4 v[188:191], v187, s[50:51]
	v_mov_b32_e32 v173, v211
	v_mov_b32_e32 v174, v211
	v_mov_b32_e32 v175, v211
	v_mov_b32_e32 v176, v211
	v_mov_b32_e32 v177, v211
	v_mov_b32_e32 v178, v211
	v_mov_b32_e32 v179, v211
	v_pk_mul_f32 v[170:171], v[124:125], v[170:171]
	v_pk_mul_f32 v[168:169], v[126:127], v[168:169]
	v_mov_b32_e32 v184, v211
	v_mov_b32_e32 v185, v211
	s_movk_i32 s16, 0x7ff
	v_cndmask_b32_e64 v172, v144, v156, s[4:5]
	v_cndmask_b32_e64 v156, v156, v144, s[0:1]
	s_nop 0
	v_mov_b32_dpp v173, v172 row_ror:1 row_mask:0xf bank_mask:0xf
	v_mov_b32_e32 v172, v211
	s_nop 1
	v_mov_b32_dpp v172, v156 row_ror:2 row_mask:0xf bank_mask:0xf
	v_cndmask_b32_e64 v156, v145, v157, s[4:5]
	v_cndmask_b32_e64 v157, v157, v145, s[0:1]
	v_lshlrev_b32_e32 v180, 16, v172
	v_mov_b32_dpp v174, v156 row_ror:1 row_mask:0xf bank_mask:0xf
	v_mov_b32_dpp v175, v157 row_ror:2 row_mask:0xf bank_mask:0xf
	v_cndmask_b32_e64 v156, v146, v158, s[4:5]
	v_cndmask_b32_e64 v157, v158, v146, s[0:1]
	v_lshlrev_b32_e32 v158, 16, v144
	v_mov_b32_dpp v176, v156 row_ror:1 row_mask:0xf bank_mask:0xf
	v_mov_b32_dpp v177, v157 row_ror:2 row_mask:0xf bank_mask:0xf
	v_cndmask_b32_e64 v156, v147, v159, s[4:5]
	v_cndmask_b32_e64 v157, v159, v147, s[0:1]
	v_lshlrev_b32_e32 v159, 16, v173
	v_mov_b32_dpp v178, v156 row_ror:1 row_mask:0xf bank_mask:0xf
	v_mov_b32_dpp v179, v157 row_ror:2 row_mask:0xf bank_mask:0xf
	v_mov_b32_e32 v156, v152
	v_mov_b32_e32 v157, v140
	v_pk_mul_f32 v[158:159], v[156:157], v[158:159]
	v_and_b32_e32 v172, 0xffff0000, v172
	v_fma_f32 v140, v136, v180, v159
	v_add_f32_e32 v180, v158, v140
	v_and_b32_e32 v159, 0xffff0000, v173
	v_and_b32_e32 v158, 0xffff0000, v144
	v_mov_b32_e32 v140, v153
	v_pk_mul_f32 v[152:153], v[140:141], v[158:159]
	v_lshlrev_b32_e32 v158, 16, v145
	v_fma_f32 v153, v137, v172, v153
	v_add_f32_e32 v172, v152, v153
	v_lshlrev_b32_e32 v159, 16, v174
	v_mov_b32_e32 v152, v154
	v_mov_b32_e32 v153, v142
	v_lshlrev_b32_e32 v173, 16, v175
	v_pk_mul_f32 v[158:159], v[152:153], v[158:159]
	v_and_b32_e32 v175, 0xffff0000, v175
	v_fma_f32 v142, v138, v173, v159
	v_add_f32_e32 v173, v158, v142
	v_and_b32_e32 v159, 0xffff0000, v174
	v_and_b32_e32 v158, 0xffff0000, v145
	v_mov_b32_e32 v142, v155
	v_pk_mul_f32 v[154:155], v[142:143], v[158:159]
	v_lshlrev_b32_e32 v158, 16, v146
	v_fma_f32 v155, v139, v175, v155
	v_add_f32_e32 v174, v154, v155
	v_lshlrev_b32_e32 v159, 16, v176
	v_mov_b32_e32 v154, v148
	v_mov_b32_e32 v155, v116
	v_lshlrev_b32_e32 v175, 16, v177
	v_pk_mul_f32 v[158:159], v[154:155], v[158:159]
	v_and_b32_e32 v177, 0xffff0000, v177
	v_fma_f32 v116, v112, v175, v159
	v_add_f32_e32 v175, v158, v116
	v_and_b32_e32 v159, 0xffff0000, v176
	v_and_b32_e32 v158, 0xffff0000, v146
	v_mov_b32_e32 v116, v149
	v_pk_mul_f32 v[148:149], v[116:117], v[158:159]
	v_mov_b32_e32 v158, v150
	v_fma_f32 v149, v113, v177, v149
	v_add_f32_e32 v176, v148, v149
	v_lshlrev_b32_e32 v148, 16, v147
	v_lshlrev_b32_e32 v149, 16, v178
	v_mov_b32_e32 v159, v118
	v_lshlrev_b32_e32 v177, 16, v179
	v_pk_mul_f32 v[148:149], v[158:159], v[148:149]
	v_and_b32_e32 v150, 0xffff0000, v179
	v_fma_f32 v118, v114, v177, v149
	v_add_f32_e32 v177, v148, v118
	v_and_b32_e32 v149, 0xffff0000, v178
	v_and_b32_e32 v148, 0xffff0000, v147
	v_mov_b32_e32 v118, v151
	v_pk_mul_f32 v[148:149], v[118:119], v[148:149]
	v_mov_b32_e32 v179, v211
	v_fma_f32 v149, v115, v150, v149
	v_add_f32_e32 v178, v148, v149
	v_pk_mul_f32 v[148:149], v[132:133], v[164:165]
	v_pk_mul_f32 v[150:151], v[134:135], v[166:167]
	v_mul_f32_e32 v148, v148, v180
	v_mul_f32_e32 v149, v149, v172
	v_cvt_pk_bf16_f32 v148, v148, v149
	v_mul_f32_e32 v149, v150, v173
	v_mul_f32_e32 v150, v151, v174
	v_cvt_pk_bf16_f32 v149, v149, v150
	v_mul_f32_e32 v150, v170, v175
	v_mul_f32_e32 v151, v171, v176
	v_cvt_pk_bf16_f32 v150, v150, v151
	v_mul_f32_e32 v151, v168, v177
	v_mul_f32_e32 v164, v169, v178
	v_cvt_pk_bf16_f32 v151, v151, v164
	v_lshlrev_b64 v[164:165], 12, v[162:163]
	v_lshl_add_u64 v[164:165], s[12:13], 0, v[164:165]
	v_lshl_add_u64 v[164:165], v[164:165], 0, v[160:161]
	global_store_dwordx4 v[164:165], v[148:151], off offset:2048 sc1
	v_or_b32_e32 v172, 16, v162
	v_ashrrev_i32_e32 v173, 31, v172
	v_mul_f32_e32 v148, 0xbfb8aa3b, v104
	v_mul_f32_e32 v149, 0xbfb8aa3b, v105
	v_exp_f32_e32 v148, v148
	v_exp_f32_e32 v149, v149
	v_mul_f32_e32 v150, 0xbfb8aa3b, v106
	v_mul_f32_e32 v151, 0xbfb8aa3b, v107
	v_exp_f32_e32 v150, v150
	v_exp_f32_e32 v151, v151
	v_add_f32_e32 v148, 1.0, v148
	v_add_f32_e32 v149, 1.0, v149
	v_rcp_f32_e32 v148, v148
	v_rcp_f32_e32 v149, v149
	v_add_f32_e32 v150, 1.0, v150
	v_add_f32_e32 v151, 1.0, v151
	v_rcp_f32_e32 v150, v150
	v_rcp_f32_e32 v151, v151
	v_pk_mul_f32 v[164:165], v[104:105], v[148:149]
	v_mul_f32_e32 v148, 0xbfb8aa3b, v96
	v_mul_f32_e32 v149, 0xbfb8aa3b, v97
	v_exp_f32_e32 v148, v148
	v_exp_f32_e32 v149, v149
	v_pk_mul_f32 v[166:167], v[106:107], v[150:151]
	v_mul_f32_e32 v150, 0xbfb8aa3b, v98
	v_mul_f32_e32 v151, 0xbfb8aa3b, v99
	v_exp_f32_e32 v150, v150
	v_exp_f32_e32 v151, v151
	v_add_f32_e32 v148, 1.0, v148
	v_add_f32_e32 v149, 1.0, v149
	v_rcp_f32_e32 v148, v148
	v_rcp_f32_e32 v149, v149
	v_add_f32_e32 v150, 1.0, v150
	v_add_f32_e32 v151, 1.0, v151
	v_rcp_f32_e32 v150, v150
	v_rcp_f32_e32 v151, v151
	v_pk_mul_f32 v[168:169], v[96:97], v[148:149]
	v_lshlrev_b64 v[148:149], 11, v[172:173]
	v_lshl_add_u64 v[148:149], s[50:51], 0, v[148:149]
	v_lshl_add_u64 v[148:149], v[148:149], 0, v[160:161]
	v_pk_mul_f32 v[170:171], v[98:99], v[150:151]
	s_waitcnt vmcnt(5)
	v_mov_b32_e32 v148, v192
	v_mov_b32_e32 v149, v193
	v_mov_b32_e32 v150, v194
	v_mov_b32_e32 v151, v195
	v_add_u32_e32 v187, 0x8000, v187
	global_load_dwordx4 v[192:195], v187, s[50:51]
	v_mov_b32_e32 v174, v211
	v_mov_b32_e32 v175, v211
	v_mov_b32_e32 v176, v211
	v_mov_b32_e32 v177, v211
	v_mov_b32_e32 v178, v211
	v_mov_b32_e32 v180, v211
	v_pk_mul_f32 v[166:167], v[110:111], v[166:167]
	v_pk_mul_f32 v[170:171], v[102:103], v[170:171]
	v_cndmask_b32_e64 v163, v148, v144, s[4:5]
	v_cndmask_b32_e64 v144, v144, v148, s[0:1]
	s_nop 0
	v_mov_b32_dpp v174, v163 row_ror:1 row_mask:0xf bank_mask:0xf
	v_mov_b32_e32 v163, v211
	s_nop 1
	v_mov_b32_dpp v163, v144 row_ror:2 row_mask:0xf bank_mask:0xf
	v_cndmask_b32_e64 v144, v149, v145, s[4:5]
	v_cndmask_b32_e64 v145, v145, v149, s[0:1]
	s_nop 0
	v_mov_b32_dpp v175, v144 row_ror:1 row_mask:0xf bank_mask:0xf
	v_mov_b32_dpp v176, v145 row_ror:2 row_mask:0xf bank_mask:0xf
	v_cndmask_b32_e64 v144, v150, v146, s[4:5]
	v_cndmask_b32_e64 v145, v146, v150, s[0:1]
	s_nop 0
	v_mov_b32_dpp v177, v144 row_ror:1 row_mask:0xf bank_mask:0xf
	v_mov_b32_dpp v178, v145 row_ror:2 row_mask:0xf bank_mask:0xf
	v_cndmask_b32_e64 v144, v151, v147, s[4:5]
	v_cndmask_b32_e64 v145, v147, v151, s[0:1]
	v_pk_mul_f32 v[146:147], v[100:101], v[168:169]
	v_mov_b32_dpp v179, v144 row_ror:1 row_mask:0xf bank_mask:0xf
	v_mov_b32_dpp v180, v145 row_ror:2 row_mask:0xf bank_mask:0xf
	v_lshlrev_b32_e32 v145, 16, v174
	v_lshlrev_b32_e32 v144, 16, v148
	v_lshlrev_b32_e32 v168, 16, v163
	v_pk_mul_f32 v[144:145], v[156:157], v[144:145]
	v_and_b32_e32 v163, 0xffff0000, v163
	v_fma_f32 v145, v136, v168, v145
	v_add_f32_e32 v168, v144, v145
	v_and_b32_e32 v145, 0xffff0000, v174
	v_and_b32_e32 v144, 0xffff0000, v148
	v_pk_mul_f32 v[144:145], v[140:141], v[144:145]
	v_lshlrev_b32_e32 v169, 16, v176
	v_fma_f32 v145, v137, v163, v145
	v_add_f32_e32 v163, v144, v145
	v_lshlrev_b32_e32 v145, 16, v175
	v_lshlrev_b32_e32 v144, 16, v149
	v_pk_mul_f32 v[144:145], v[152:153], v[144:145]
	v_and_b32_e32 v174, 0xffff0000, v176
	v_fma_f32 v145, v138, v169, v145
	v_add_f32_e32 v169, v144, v145
	v_and_b32_e32 v145, 0xffff0000, v175
	v_and_b32_e32 v144, 0xffff0000, v149
	v_pk_mul_f32 v[144:145], v[142:143], v[144:145]
	v_lshlrev_b32_e32 v175, 16, v178
	v_fma_f32 v145, v139, v174, v145
	v_add_f32_e32 v174, v144, v145
	v_lshlrev_b32_e32 v145, 16, v177
	v_lshlrev_b32_e32 v144, 16, v150
	v_pk_mul_f32 v[144:145], v[154:155], v[144:145]
	v_and_b32_e32 v176, 0xffff0000, v178
	v_fma_f32 v145, v112, v175, v145
	v_add_f32_e32 v175, v144, v145
	v_and_b32_e32 v145, 0xffff0000, v177
	v_and_b32_e32 v144, 0xffff0000, v150
	v_pk_mul_f32 v[144:145], v[116:117], v[144:145]
	v_lshlrev_b32_e32 v177, 16, v180
	v_fma_f32 v145, v113, v176, v145
	v_add_f32_e32 v176, v144, v145
	v_lshlrev_b32_e32 v145, 16, v179
	v_lshlrev_b32_e32 v144, 16, v151
	v_pk_mul_f32 v[144:145], v[158:159], v[144:145]
	v_and_b32_e32 v178, 0xffff0000, v180
	v_fma_f32 v145, v114, v177, v145
	v_add_f32_e32 v177, v144, v145
	v_and_b32_e32 v145, 0xffff0000, v179
	v_and_b32_e32 v144, 0xffff0000, v151
	v_pk_mul_f32 v[144:145], v[118:119], v[144:145]
	v_mul_f32_e32 v146, v146, v175
	v_fma_f32 v145, v115, v178, v145
	v_add_f32_e32 v178, v144, v145
	v_pk_mul_f32 v[144:145], v[108:109], v[164:165]
	v_lshlrev_b64 v[164:165], 12, v[172:173]
	v_mul_f32_e32 v144, v144, v168
	v_mul_f32_e32 v145, v145, v163
	v_cvt_pk_bf16_f32 v144, v144, v145
	v_mul_f32_e32 v145, v166, v169
	v_mul_f32_e32 v147, v147, v176
	v_lshl_add_u64 v[164:165], s[12:13], 0, v[164:165]
	v_mul_f32_e32 v163, v167, v174
	v_cvt_pk_bf16_f32 v145, v145, v163
	v_cvt_pk_bf16_f32 v146, v146, v147
	v_mul_f32_e32 v147, v170, v177
	v_lshl_add_u64 v[164:165], v[164:165], 0, v[160:161]
	v_mul_f32_e32 v163, v171, v178
	v_cvt_pk_bf16_f32 v147, v147, v163
	global_store_dwordx4 v[164:165], v[144:147], off offset:2048 sc1
	v_or_b32_e32 v172, 32, v162
	v_ashrrev_i32_e32 v173, 31, v172
	v_mul_f32_e32 v144, 0xbfb8aa3b, v88
	v_mul_f32_e32 v145, 0xbfb8aa3b, v89
	v_exp_f32_e32 v144, v144
	v_exp_f32_e32 v145, v145
	v_mul_f32_e32 v146, 0xbfb8aa3b, v90
	v_mul_f32_e32 v147, 0xbfb8aa3b, v91
	v_exp_f32_e32 v146, v146
	v_exp_f32_e32 v147, v147
	v_add_f32_e32 v144, 1.0, v144
	v_add_f32_e32 v145, 1.0, v145
	v_rcp_f32_e32 v144, v144
	v_rcp_f32_e32 v145, v145
	v_add_f32_e32 v146, 1.0, v146
	v_add_f32_e32 v147, 1.0, v147
	v_rcp_f32_e32 v146, v146
	v_rcp_f32_e32 v147, v147
	v_pk_mul_f32 v[164:165], v[88:89], v[144:145]
	v_mul_f32_e32 v144, 0xbfb8aa3b, v80
	v_mul_f32_e32 v145, 0xbfb8aa3b, v81
	v_exp_f32_e32 v144, v144
	v_exp_f32_e32 v145, v145
	v_pk_mul_f32 v[166:167], v[90:91], v[146:147]
	v_mul_f32_e32 v146, 0xbfb8aa3b, v82
	v_mul_f32_e32 v147, 0xbfb8aa3b, v83
	v_exp_f32_e32 v146, v146
	v_exp_f32_e32 v147, v147
	v_add_f32_e32 v144, 1.0, v144
	v_add_f32_e32 v145, 1.0, v145
	v_rcp_f32_e32 v144, v144
	v_rcp_f32_e32 v145, v145
	v_add_f32_e32 v146, 1.0, v146
	v_add_f32_e32 v147, 1.0, v147
	v_rcp_f32_e32 v146, v146
	v_rcp_f32_e32 v147, v147
	v_pk_mul_f32 v[168:169], v[80:81], v[144:145]
	v_lshlrev_b64 v[144:145], 11, v[172:173]
	v_lshl_add_u64 v[144:145], s[50:51], 0, v[144:145]
	v_lshl_add_u64 v[144:145], v[144:145], 0, v[160:161]
	v_pk_mul_f32 v[170:171], v[82:83], v[146:147]
	s_waitcnt vmcnt(6)
	v_mov_b32_e32 v144, v196
	v_mov_b32_e32 v145, v197
	v_mov_b32_e32 v146, v198
	v_mov_b32_e32 v147, v199
	v_add_u32_e32 v187, 0x8000, v187
	global_load_dwordx4 v[196:199], v187, s[50:51]
	v_mov_b32_e32 v174, v211
	v_mov_b32_e32 v175, v211
	v_mov_b32_e32 v176, v211
	v_mov_b32_e32 v177, v211
	v_mov_b32_e32 v178, v211
	v_mov_b32_e32 v179, v211
	v_mov_b32_e32 v180, v211
	v_pk_mul_f32 v[166:167], v[94:95], v[166:167]
	v_pk_mul_f32 v[170:171], v[86:87], v[170:171]
	v_cndmask_b32_e64 v163, v144, v148, s[4:5]
	v_cndmask_b32_e64 v148, v148, v144, s[0:1]
	s_nop 0
	v_mov_b32_dpp v174, v163 row_ror:1 row_mask:0xf bank_mask:0xf
	v_mov_b32_e32 v163, v211
	s_nop 1
	v_mov_b32_dpp v163, v148 row_ror:2 row_mask:0xf bank_mask:0xf
	v_cndmask_b32_e64 v148, v145, v149, s[4:5]
	v_cndmask_b32_e64 v149, v149, v145, s[0:1]
	s_nop 0
	v_mov_b32_dpp v175, v148 row_ror:1 row_mask:0xf bank_mask:0xf
	v_mov_b32_dpp v176, v149 row_ror:2 row_mask:0xf bank_mask:0xf
	v_cndmask_b32_e64 v148, v146, v150, s[4:5]
	v_cndmask_b32_e64 v149, v150, v146, s[0:1]
	s_nop 0
	v_mov_b32_dpp v177, v148 row_ror:1 row_mask:0xf bank_mask:0xf
	v_mov_b32_dpp v178, v149 row_ror:2 row_mask:0xf bank_mask:0xf
	v_cndmask_b32_e64 v148, v147, v151, s[4:5]
	v_cndmask_b32_e64 v149, v151, v147, s[0:1]
	v_pk_mul_f32 v[150:151], v[84:85], v[168:169]
	v_mov_b32_dpp v179, v148 row_ror:1 row_mask:0xf bank_mask:0xf
	v_mov_b32_dpp v180, v149 row_ror:2 row_mask:0xf bank_mask:0xf
	v_lshlrev_b32_e32 v149, 16, v174
	v_lshlrev_b32_e32 v148, 16, v144
	v_lshlrev_b32_e32 v168, 16, v163
	v_pk_mul_f32 v[148:149], v[156:157], v[148:149]
	v_and_b32_e32 v163, 0xffff0000, v163
	v_fma_f32 v149, v136, v168, v149
	v_add_f32_e32 v168, v148, v149
	v_and_b32_e32 v149, 0xffff0000, v174
	v_and_b32_e32 v148, 0xffff0000, v144
	v_pk_mul_f32 v[148:149], v[140:141], v[148:149]
	v_lshlrev_b32_e32 v169, 16, v176
	v_fma_f32 v149, v137, v163, v149
	v_add_f32_e32 v163, v148, v149
	v_lshlrev_b32_e32 v149, 16, v175
	v_lshlrev_b32_e32 v148, 16, v145
	v_pk_mul_f32 v[148:149], v[152:153], v[148:149]
	v_and_b32_e32 v174, 0xffff0000, v176
	v_fma_f32 v149, v138, v169, v149
	v_add_f32_e32 v169, v148, v149
	v_and_b32_e32 v149, 0xffff0000, v175
	v_and_b32_e32 v148, 0xffff0000, v145
	v_pk_mul_f32 v[148:149], v[142:143], v[148:149]
	v_lshlrev_b32_e32 v175, 16, v178
	v_fma_f32 v149, v139, v174, v149
	v_add_f32_e32 v174, v148, v149
	v_lshlrev_b32_e32 v149, 16, v177
	v_lshlrev_b32_e32 v148, 16, v146
	v_pk_mul_f32 v[148:149], v[154:155], v[148:149]
	v_and_b32_e32 v176, 0xffff0000, v178
	v_fma_f32 v149, v112, v175, v149
	v_add_f32_e32 v175, v148, v149
	v_and_b32_e32 v149, 0xffff0000, v177
	v_and_b32_e32 v148, 0xffff0000, v146
	v_pk_mul_f32 v[148:149], v[116:117], v[148:149]
	v_lshlrev_b32_e32 v177, 16, v180
	v_fma_f32 v149, v113, v176, v149
	v_add_f32_e32 v176, v148, v149
	v_lshlrev_b32_e32 v149, 16, v179
	v_lshlrev_b32_e32 v148, 16, v147
	v_pk_mul_f32 v[148:149], v[158:159], v[148:149]
	v_and_b32_e32 v178, 0xffff0000, v180
	v_fma_f32 v149, v114, v177, v149
	v_add_f32_e32 v177, v148, v149
	v_and_b32_e32 v149, 0xffff0000, v179
	v_and_b32_e32 v148, 0xffff0000, v147
	v_pk_mul_f32 v[148:149], v[118:119], v[148:149]
	v_mul_f32_e32 v150, v150, v175
	v_fma_f32 v149, v115, v178, v149
	v_add_f32_e32 v178, v148, v149
	v_pk_mul_f32 v[148:149], v[92:93], v[164:165]
	v_mul_f32_e32 v151, v151, v176
	v_mul_f32_e32 v148, v148, v168
	v_mul_f32_e32 v149, v149, v163
	v_or_b32_e32 v168, 48, v162
	v_cvt_pk_bf16_f32 v148, v148, v149
	v_mul_f32_e32 v149, v166, v169
	v_mul_f32_e32 v163, v167, v174
	v_lshlrev_b64 v[164:165], 12, v[172:173]
	v_ashrrev_i32_e32 v169, 31, v168
	v_cvt_pk_bf16_f32 v149, v149, v163
	v_cvt_pk_bf16_f32 v150, v150, v151
	v_mul_f32_e32 v151, v170, v177
	v_mul_f32_e32 v163, v171, v178
	v_lshl_add_u64 v[164:165], s[12:13], 0, v[164:165]
	v_lshlrev_b64 v[170:171], 11, v[168:169]
	v_lshl_add_u64 v[164:165], v[164:165], 0, v[160:161]
	v_lshl_add_u64 v[170:171], s[50:51], 0, v[170:171]
	v_cvt_pk_bf16_f32 v151, v151, v163
	global_store_dwordx4 v[164:165], v[148:151], off offset:2048 sc1
	v_lshl_add_u64 v[170:171], v[170:171], 0, v[160:161]
	s_waitcnt vmcnt(7)
	v_mov_b32_e32 v176, v228
	v_mov_b32_e32 v177, v229
	v_mov_b32_e32 v178, v230
	v_mov_b32_e32 v179, v231
	v_mul_f32_e32 v148, 0xbfb8aa3b, v72
	v_mul_f32_e32 v149, 0xbfb8aa3b, v73
	v_exp_f32_e32 v148, v148
	v_exp_f32_e32 v149, v149
	v_mul_f32_e32 v150, 0xbfb8aa3b, v74
	v_mul_f32_e32 v151, 0xbfb8aa3b, v75
	v_add_f32_e32 v148, 1.0, v148
	v_add_f32_e32 v149, 1.0, v149
	v_rcp_f32_e32 v148, v148
	v_rcp_f32_e32 v149, v149
	v_exp_f32_e32 v150, v150
	v_exp_f32_e32 v151, v151
	v_mov_b32_e32 v170, v211
	v_pk_mul_f32 v[164:165], v[72:73], v[148:149]
	v_mul_f32_e32 v148, 0xbfb8aa3b, v64
	v_mul_f32_e32 v149, 0xbfb8aa3b, v65
	v_exp_f32_e32 v148, v148
	v_exp_f32_e32 v149, v149
	v_add_f32_e32 v150, 1.0, v150
	v_add_f32_e32 v151, 1.0, v151
	v_add_f32_e32 v148, 1.0, v148
	v_add_f32_e32 v149, 1.0, v149
	v_rcp_f32_e32 v148, v148
	v_rcp_f32_e32 v149, v149
	v_rcp_f32_e32 v150, v150
	v_rcp_f32_e32 v151, v151
	v_mov_b32_e32 v172, v211
	v_mov_b32_e32 v173, v211
	v_mov_b32_e32 v174, v211
	v_mov_b32_e32 v175, v211
	v_pk_mul_f32 v[148:149], v[64:65], v[148:149]
	v_pk_mul_f32 v[166:167], v[74:75], v[150:151]
	v_mul_f32_e32 v150, 0xbfb8aa3b, v66
	v_mul_f32_e32 v151, 0xbfb8aa3b, v67
	v_pk_mul_f32 v[182:183], v[68:69], v[148:149]
	v_exp_f32_e32 v150, v150
	v_exp_f32_e32 v151, v151
	v_pk_mul_f32 v[164:165], v[76:77], v[164:165]
	v_pk_mul_f32 v[166:167], v[78:79], v[166:167]
	v_add_f32_e32 v150, 1.0, v150
	v_add_f32_e32 v151, 1.0, v151
	v_rcp_f32_e32 v150, v150
	v_rcp_f32_e32 v151, v151
	v_cndmask_b32_e64 v163, v176, v144, s[4:5]
	v_cndmask_b32_e64 v144, v144, v176, s[0:1]
	s_nop 0
	v_mov_b32_dpp v170, v163 row_ror:1 row_mask:0xf bank_mask:0xf
	v_mov_b32_e32 v163, v211
	v_and_b32_e32 v171, 0xffff0000, v170
	v_pk_mul_f32 v[150:151], v[66:67], v[150:151]
	v_mov_b32_dpp v163, v144 row_ror:2 row_mask:0xf bank_mask:0xf
	v_cndmask_b32_e64 v144, v177, v145, s[4:5]
	v_cndmask_b32_e64 v145, v145, v177, s[0:1]
	v_lshlrev_b32_e32 v148, 16, v163
	v_mov_b32_dpp v172, v144 row_ror:1 row_mask:0xf bank_mask:0xf
	v_mov_b32_dpp v173, v145 row_ror:2 row_mask:0xf bank_mask:0xf
	v_cndmask_b32_e64 v144, v178, v146, s[4:5]
	v_cndmask_b32_e64 v145, v146, v178, s[0:1]
	v_pk_mul_f32 v[180:181], v[70:71], v[150:151]
	v_mov_b32_dpp v174, v144 row_ror:1 row_mask:0xf bank_mask:0xf
	v_mov_b32_dpp v175, v145 row_ror:2 row_mask:0xf bank_mask:0xf
	v_cndmask_b32_e64 v144, v179, v147, s[4:5]
	v_cndmask_b32_e64 v145, v147, v179, s[0:1]
	s_nop 0
	v_mov_b32_dpp v184, v144 row_ror:1 row_mask:0xf bank_mask:0xf
	v_mov_b32_dpp v185, v145 row_ror:2 row_mask:0xf bank_mask:0xf
	v_lshlrev_b32_e32 v145, 16, v170
	v_lshlrev_b32_e32 v144, 16, v176
	v_pk_mul_f32 v[146:147], v[156:157], v[144:145]
	v_and_b32_e32 v170, 0xffff0000, v176
	v_fma_f32 v145, v136, v148, v147
	v_add_f32_e32 v186, v146, v145
	v_and_b32_e32 v145, 0xffff0000, v163
	v_pk_mul_f32 v[146:147], v[140:141], v[170:171]
	s_nop 0
	v_fma_f32 v145, v137, v145, v147
	v_add_f32_e32 v163, v146, v145
	v_lshlrev_b32_e32 v147, 16, v172
	v_lshlrev_b32_e32 v146, 16, v177
	v_lshlrev_b32_e32 v145, 16, v173
	v_pk_mul_f32 v[148:149], v[152:153], v[146:147]
	v_mul_f32_e32 v163, v165, v163
	v_fma_f32 v145, v138, v145, v149
	v_add_f32_e32 v147, v148, v145
	v_and_b32_e32 v145, 0xffff0000, v173
	v_and_b32_e32 v173, 0xffff0000, v172
	v_and_b32_e32 v172, 0xffff0000, v177
	v_pk_mul_f32 v[148:149], v[142:143], v[172:173]
	v_mul_f32_e32 v147, v166, v147
	v_fma_f32 v145, v139, v145, v149
	v_add_f32_e32 v171, v148, v145
	v_lshlrev_b32_e32 v149, 16, v174
	v_lshlrev_b32_e32 v148, 16, v178
	v_lshlrev_b32_e32 v145, 16, v175
	v_pk_mul_f32 v[150:151], v[154:155], v[148:149]
	s_nop 0
	v_fma_f32 v145, v112, v145, v151
	v_add_f32_e32 v149, v150, v145
	v_and_b32_e32 v145, 0xffff0000, v175
	v_and_b32_e32 v175, 0xffff0000, v174
	v_and_b32_e32 v174, 0xffff0000, v178
	v_pk_mul_f32 v[150:151], v[116:117], v[174:175]
	s_nop 0
	v_fma_f32 v145, v113, v145, v151
	v_add_f32_e32 v173, v150, v145
	v_lshlrev_b32_e32 v151, 16, v184
	v_lshlrev_b32_e32 v150, 16, v179
	v_lshlrev_b32_e32 v145, 16, v185
	v_pk_mul_f32 v[176:177], v[158:159], v[150:151]
	s_nop 0
	v_fma_f32 v145, v114, v145, v177
	v_add_f32_e32 v151, v176, v145
	v_and_b32_e32 v177, 0xffff0000, v184
	v_and_b32_e32 v176, 0xffff0000, v179
	v_and_b32_e32 v145, 0xffff0000, v185
	v_pk_mul_f32 v[178:179], v[118:119], v[176:177]
	s_nop 0
	v_fma_f32 v145, v115, v145, v179
	v_add_f32_e32 v175, v178, v145
	v_bitop3_b32 v145, v162, s16, 48 bitop3:0xc8
	v_mul_f32_e32 v162, v164, v186
	v_cvt_pk_bf16_f32 v162, v162, v163
	v_mul_f32_e32 v163, v167, v171
	v_lshlrev_b64 v[166:167], 12, v[168:169]
	v_lshl_add_u64 v[166:167], s[12:13], 0, v[166:167]
	s_movk_i32 s16, 0x7fd
	v_cvt_pk_bf16_f32 v163, v147, v163
	v_mul_f32_e32 v147, v182, v149
	v_mul_f32_e32 v149, v183, v173
	v_lshl_add_u64 v[166:167], v[166:167], 0, v[160:161]
	v_cmp_lt_u32_e32 vcc, s16, v145
	v_cvt_pk_bf16_f32 v164, v147, v149
	v_mul_f32_e32 v147, v180, v151
	v_mul_f32_e32 v149, v181, v175
	v_cvt_pk_bf16_f32 v165, v147, v149
	global_store_dwordx4 v[166:167], v[162:165], off offset:2048 sc1
	s_and_saveexec_b64 s[40:41], vcc
	s_cbranch_execz .LBB0_316
	v_lshrrev_b32_e32 v147, 21, v169
	v_add_u32_e32 v147, v168, v147
	v_ashrrev_i32_e32 v162, 11, v147
	v_ashrrev_i32_e32 v163, 31, v162
	v_add_u32_e32 v164, 0xfffff802, v145
	v_mov_b32_e32 v165, v211
	v_lshlrev_b64 v[162:163], 13, v[162:163]
	v_lshl_add_u64 v[162:163], s[18:19], 0, v[162:163]
	v_lshlrev_b64 v[164:165], 12, v[164:165]
	v_lshl_add_u64 v[162:163], v[162:163], 0, v[164:165]
	v_lshl_add_u64 v[162:163], v[210:211], 2, v[162:163]
	v_mov_b32_e32 v145, v170
	v_mov_b32_e32 v147, v172
	v_mov_b32_e32 v149, v174
	v_mov_b32_e32 v151, v176
	global_store_dwordx4 v[162:163], v[144:147], off
	global_store_dwordx4 v[162:163], v[148:151], off offset:16
.LBB0_316:
	s_or_b64 exec, exec, s[40:41]
	s_addk_i32 s11, 0x80
	s_and_b32 s16, s11, 0x7c0
	s_cmp_lg_u32 s16, 0
	s_cselect_b64 s[16:17], -1, 0
	s_and_b64 s[16:17], s[8:9], s[16:17]
	v_mov_b32_e32 v148, 0
	v_mov_b32_e32 v149, 0
	v_mov_b32_e32 v150, 0
	v_mov_b32_e32 v151, 0
	v_mov_b32_e32 v148, v250
	v_mov_b32_e32 v149, v251
	v_mov_b32_e32 v150, v252
	v_mov_b32_e32 v151, v253
	v_mul_f32_e32 v144, 0xbfb8aa3b, v56
	v_mul_f32_e32 v145, 0xbfb8aa3b, v57
	v_exp_f32_e32 v144, v144
	v_exp_f32_e32 v145, v145
	v_mul_f32_e32 v146, 0xbfb8aa3b, v58
	v_mul_f32_e32 v147, 0xbfb8aa3b, v59
	v_exp_f32_e32 v146, v146
	v_exp_f32_e32 v147, v147
	v_add_f32_e32 v144, 1.0, v144
	v_add_f32_e32 v145, 1.0, v145
	v_rcp_f32_e32 v144, v144
	v_rcp_f32_e32 v145, v145
	v_add_f32_e32 v146, 1.0, v146
	v_add_f32_e32 v147, 1.0, v147
	v_rcp_f32_e32 v146, v146
	v_rcp_f32_e32 v147, v147
	v_pk_mul_f32 v[164:165], v[56:57], v[144:145]
	v_mul_f32_e32 v144, 0xbfb8aa3b, v48
	v_mul_f32_e32 v145, 0xbfb8aa3b, v49
	v_exp_f32_e32 v144, v144
	v_exp_f32_e32 v145, v145
	v_pk_mul_f32 v[166:167], v[58:59], v[146:147]
	v_mul_f32_e32 v146, 0xbfb8aa3b, v50
	v_mul_f32_e32 v147, 0xbfb8aa3b, v51
	v_exp_f32_e32 v146, v146
	v_exp_f32_e32 v147, v147
	v_add_f32_e32 v144, 1.0, v144
	v_add_f32_e32 v145, 1.0, v145
	v_rcp_f32_e32 v144, v144
	v_rcp_f32_e32 v145, v145
	v_or_b32_e32 v162, s11, v233
	v_add_f32_e32 v146, 1.0, v146
	v_add_f32_e32 v147, 1.0, v147
	v_rcp_f32_e32 v146, v146
	v_rcp_f32_e32 v147, v147
	v_ashrrev_i32_e32 v163, 31, v162
	v_pk_mul_f32 v[168:169], v[48:49], v[144:145]
	v_lshlrev_b64 v[144:145], 11, v[162:163]
	v_lshl_add_u64 v[144:145], s[50:51], 0, v[144:145]
	v_lshl_add_u64 v[144:145], v[144:145], 0, v[160:161]
	v_pk_mul_f32 v[170:171], v[50:51], v[146:147]
	s_waitcnt vmcnt(7)
	v_mov_b32_e32 v144, v246
	v_mov_b32_e32 v145, v247
	v_mov_b32_e32 v146, v248
	v_mov_b32_e32 v147, v249
	v_mov_b32_e32 v173, v211
	v_mov_b32_e32 v174, v211
	v_mov_b32_e32 v175, v211
	v_mov_b32_e32 v176, v211
	v_mov_b32_e32 v177, v211
	v_mov_b32_e32 v178, v211
	v_mov_b32_e32 v179, v211
	v_pk_mul_f32 v[166:167], v[62:63], v[166:167]
	v_pk_mul_f32 v[170:171], v[54:55], v[170:171]
	v_mov_b32_e32 v180, v211
	s_movk_i32 s8, 0x7ff
	v_cndmask_b32_e64 v172, v144, v148, s[4:5]
	v_cndmask_b32_e64 v148, v148, v144, s[0:1]
	s_nop 0
	v_mov_b32_dpp v173, v172 row_ror:1 row_mask:0xf bank_mask:0xf
	v_mov_b32_e32 v172, v211
	s_nop 1
	v_mov_b32_dpp v172, v148 row_ror:2 row_mask:0xf bank_mask:0xf
	v_cndmask_b32_e64 v148, v145, v149, s[4:5]
	v_cndmask_b32_e64 v149, v149, v145, s[0:1]
	s_nop 0
	v_mov_b32_dpp v174, v148 row_ror:1 row_mask:0xf bank_mask:0xf
	v_mov_b32_dpp v175, v149 row_ror:2 row_mask:0xf bank_mask:0xf
	v_cndmask_b32_e64 v148, v146, v150, s[4:5]
	v_cndmask_b32_e64 v149, v150, v146, s[0:1]
	s_nop 0
	v_mov_b32_dpp v176, v148 row_ror:1 row_mask:0xf bank_mask:0xf
	v_mov_b32_dpp v177, v149 row_ror:2 row_mask:0xf bank_mask:0xf
	v_cndmask_b32_e64 v148, v147, v151, s[4:5]
	v_cndmask_b32_e64 v149, v151, v147, s[0:1]
	v_pk_mul_f32 v[150:151], v[52:53], v[168:169]
	v_mov_b32_dpp v178, v148 row_ror:1 row_mask:0xf bank_mask:0xf
	v_mov_b32_dpp v179, v149 row_ror:2 row_mask:0xf bank_mask:0xf
	v_lshlrev_b32_e32 v148, 16, v144
	v_lshlrev_b32_e32 v149, 16, v173
	v_lshlrev_b32_e32 v168, 16, v172
	v_pk_mul_f32 v[148:149], v[156:157], v[148:149]
	v_and_b32_e32 v169, 0xffff0000, v172
	v_fma_f32 v149, v136, v168, v149
	v_add_f32_e32 v168, v148, v149
	v_and_b32_e32 v149, 0xffff0000, v173
	v_and_b32_e32 v148, 0xffff0000, v144
	v_pk_mul_f32 v[148:149], v[140:141], v[148:149]
	v_lshlrev_b32_e32 v172, 16, v175
	v_fma_f32 v149, v137, v169, v149
	v_add_f32_e32 v169, v148, v149
	v_lshlrev_b32_e32 v148, 16, v145
	v_lshlrev_b32_e32 v149, 16, v174
	v_pk_mul_f32 v[148:149], v[152:153], v[148:149]
	v_and_b32_e32 v173, 0xffff0000, v175
	v_fma_f32 v149, v138, v172, v149
	v_add_f32_e32 v172, v148, v149
	v_and_b32_e32 v149, 0xffff0000, v174
	v_and_b32_e32 v148, 0xffff0000, v145
	v_pk_mul_f32 v[148:149], v[142:143], v[148:149]
	v_lshlrev_b32_e32 v174, 16, v177
	v_fma_f32 v149, v139, v173, v149
	v_add_f32_e32 v173, v148, v149
	v_lshlrev_b32_e32 v148, 16, v146
	v_lshlrev_b32_e32 v149, 16, v176
	v_pk_mul_f32 v[148:149], v[154:155], v[148:149]
	v_and_b32_e32 v175, 0xffff0000, v177
	v_fma_f32 v149, v112, v174, v149
	v_add_f32_e32 v174, v148, v149
	v_and_b32_e32 v149, 0xffff0000, v176
	v_and_b32_e32 v148, 0xffff0000, v146
	v_pk_mul_f32 v[148:149], v[116:117], v[148:149]
	v_lshlrev_b32_e32 v176, 16, v179
	v_fma_f32 v149, v113, v175, v149
	v_add_f32_e32 v175, v148, v149
	v_lshlrev_b32_e32 v148, 16, v147
	v_lshlrev_b32_e32 v149, 16, v178
	v_pk_mul_f32 v[148:149], v[158:159], v[148:149]
	v_and_b32_e32 v177, 0xffff0000, v179
	v_fma_f32 v149, v114, v176, v149
	v_add_f32_e32 v176, v148, v149
	v_and_b32_e32 v149, 0xffff0000, v178
	v_and_b32_e32 v148, 0xffff0000, v147
	v_pk_mul_f32 v[148:149], v[118:119], v[148:149]
	v_mul_f32_e32 v150, v150, v174
	v_fma_f32 v149, v115, v177, v149
	v_add_f32_e32 v177, v148, v149
	v_pk_mul_f32 v[148:149], v[60:61], v[164:165]
	v_mul_f32_e32 v164, v167, v173
	v_mul_f32_e32 v148, v148, v168
	v_mul_f32_e32 v149, v149, v169
	v_cvt_pk_bf16_f32 v148, v148, v149
	v_mul_f32_e32 v149, v166, v172
	v_mul_f32_e32 v151, v151, v175
	v_cvt_pk_bf16_f32 v149, v149, v164
	v_cvt_pk_bf16_f32 v150, v150, v151
	v_mul_f32_e32 v151, v170, v176
	v_mul_f32_e32 v164, v171, v177
	v_cvt_pk_bf16_f32 v151, v151, v164
	v_lshlrev_b64 v[164:165], 12, v[162:163]
	v_lshl_add_u64 v[164:165], s[12:13], 0, v[164:165]
	v_lshl_add_u64 v[164:165], v[164:165], 0, v[160:161]
	global_store_dwordx4 v[164:165], v[148:151], off offset:2048 sc1
	v_or_b32_e32 v172, 16, v162
	v_ashrrev_i32_e32 v173, 31, v172
	v_mul_f32_e32 v148, 0xbfb8aa3b, v40
	v_mul_f32_e32 v149, 0xbfb8aa3b, v41
	v_exp_f32_e32 v148, v148
	v_exp_f32_e32 v149, v149
	v_mul_f32_e32 v150, 0xbfb8aa3b, v42
	v_mul_f32_e32 v151, 0xbfb8aa3b, v43
	v_exp_f32_e32 v150, v150
	v_exp_f32_e32 v151, v151
	v_add_f32_e32 v148, 1.0, v148
	v_add_f32_e32 v149, 1.0, v149
	v_rcp_f32_e32 v148, v148
	v_rcp_f32_e32 v149, v149
	v_add_f32_e32 v150, 1.0, v150
	v_add_f32_e32 v151, 1.0, v151
	v_rcp_f32_e32 v150, v150
	v_rcp_f32_e32 v151, v151
	v_pk_mul_f32 v[164:165], v[40:41], v[148:149]
	v_mul_f32_e32 v148, 0xbfb8aa3b, v32
	v_mul_f32_e32 v149, 0xbfb8aa3b, v33
	v_exp_f32_e32 v148, v148
	v_exp_f32_e32 v149, v149
	v_pk_mul_f32 v[166:167], v[42:43], v[150:151]
	v_mul_f32_e32 v150, 0xbfb8aa3b, v34
	v_mul_f32_e32 v151, 0xbfb8aa3b, v35
	v_exp_f32_e32 v150, v150
	v_exp_f32_e32 v151, v151
	v_add_f32_e32 v148, 1.0, v148
	v_add_f32_e32 v149, 1.0, v149
	v_rcp_f32_e32 v148, v148
	v_rcp_f32_e32 v149, v149
	v_add_f32_e32 v150, 1.0, v150
	v_add_f32_e32 v151, 1.0, v151
	v_rcp_f32_e32 v150, v150
	v_rcp_f32_e32 v151, v151
	v_pk_mul_f32 v[168:169], v[32:33], v[148:149]
	v_lshlrev_b64 v[148:149], 11, v[172:173]
	v_lshl_add_u64 v[148:149], s[50:51], 0, v[148:149]
	v_lshl_add_u64 v[148:149], v[148:149], 0, v[160:161]
	v_pk_mul_f32 v[170:171], v[34:35], v[150:151]
	s_waitcnt vmcnt(7)
	v_mov_b32_e32 v148, v188
	v_mov_b32_e32 v149, v189
	v_mov_b32_e32 v150, v190
	v_mov_b32_e32 v151, v191
	v_mov_b32_e32 v174, v211
	v_mov_b32_e32 v175, v211
	v_mov_b32_e32 v176, v211
	v_mov_b32_e32 v177, v211
	v_mov_b32_e32 v178, v211
	v_mov_b32_e32 v179, v211
	v_pk_mul_f32 v[166:167], v[46:47], v[166:167]
	v_pk_mul_f32 v[170:171], v[38:39], v[170:171]
	v_cndmask_b32_e64 v163, v148, v144, s[4:5]
	v_cndmask_b32_e64 v144, v144, v148, s[0:1]
	s_nop 0
	v_mov_b32_dpp v174, v163 row_ror:1 row_mask:0xf bank_mask:0xf
	v_mov_b32_e32 v163, v211
	s_nop 1
	v_mov_b32_dpp v163, v144 row_ror:2 row_mask:0xf bank_mask:0xf
	v_cndmask_b32_e64 v144, v149, v145, s[4:5]
	v_cndmask_b32_e64 v145, v145, v149, s[0:1]
	s_nop 0
	v_mov_b32_dpp v175, v144 row_ror:1 row_mask:0xf bank_mask:0xf
	v_mov_b32_dpp v176, v145 row_ror:2 row_mask:0xf bank_mask:0xf
	v_cndmask_b32_e64 v144, v150, v146, s[4:5]
	v_cndmask_b32_e64 v145, v146, v150, s[0:1]
	s_nop 0
	v_mov_b32_dpp v177, v144 row_ror:1 row_mask:0xf bank_mask:0xf
	v_mov_b32_dpp v178, v145 row_ror:2 row_mask:0xf bank_mask:0xf
	v_cndmask_b32_e64 v144, v151, v147, s[4:5]
	v_cndmask_b32_e64 v145, v147, v151, s[0:1]
	v_pk_mul_f32 v[146:147], v[36:37], v[168:169]
	v_mov_b32_dpp v179, v144 row_ror:1 row_mask:0xf bank_mask:0xf
	v_mov_b32_dpp v180, v145 row_ror:2 row_mask:0xf bank_mask:0xf
	v_lshlrev_b32_e32 v145, 16, v174
	v_lshlrev_b32_e32 v144, 16, v148
	v_lshlrev_b32_e32 v168, 16, v163
	v_pk_mul_f32 v[144:145], v[156:157], v[144:145]
	v_and_b32_e32 v163, 0xffff0000, v163
	v_fma_f32 v145, v136, v168, v145
	v_add_f32_e32 v168, v144, v145
	v_and_b32_e32 v145, 0xffff0000, v174
	v_and_b32_e32 v144, 0xffff0000, v148
	v_pk_mul_f32 v[144:145], v[140:141], v[144:145]
	v_lshlrev_b32_e32 v169, 16, v176
	v_fma_f32 v145, v137, v163, v145
	v_add_f32_e32 v163, v144, v145
	v_lshlrev_b32_e32 v145, 16, v175
	v_lshlrev_b32_e32 v144, 16, v149
	v_pk_mul_f32 v[144:145], v[152:153], v[144:145]
	v_and_b32_e32 v174, 0xffff0000, v176
	v_fma_f32 v145, v138, v169, v145
	v_add_f32_e32 v169, v144, v145
	v_and_b32_e32 v145, 0xffff0000, v175
	v_and_b32_e32 v144, 0xffff0000, v149
	v_pk_mul_f32 v[144:145], v[142:143], v[144:145]
	v_lshlrev_b32_e32 v175, 16, v178
	v_fma_f32 v145, v139, v174, v145
	v_add_f32_e32 v174, v144, v145
	v_lshlrev_b32_e32 v145, 16, v177
	v_lshlrev_b32_e32 v144, 16, v150
	v_pk_mul_f32 v[144:145], v[154:155], v[144:145]
	v_and_b32_e32 v176, 0xffff0000, v178
	v_fma_f32 v145, v112, v175, v145
	v_add_f32_e32 v175, v144, v145
	v_and_b32_e32 v145, 0xffff0000, v177
	v_and_b32_e32 v144, 0xffff0000, v150
	v_pk_mul_f32 v[144:145], v[116:117], v[144:145]
	v_lshlrev_b32_e32 v177, 16, v180
	v_fma_f32 v145, v113, v176, v145
	v_add_f32_e32 v176, v144, v145
	v_lshlrev_b32_e32 v145, 16, v179
	v_lshlrev_b32_e32 v144, 16, v151
	v_pk_mul_f32 v[144:145], v[158:159], v[144:145]
	v_and_b32_e32 v178, 0xffff0000, v180
	v_fma_f32 v145, v114, v177, v145
	v_add_f32_e32 v177, v144, v145
	v_and_b32_e32 v145, 0xffff0000, v179
	v_and_b32_e32 v144, 0xffff0000, v151
	v_pk_mul_f32 v[144:145], v[118:119], v[144:145]
	v_mul_f32_e32 v146, v146, v175
	v_fma_f32 v145, v115, v178, v145
	v_add_f32_e32 v178, v144, v145
	v_pk_mul_f32 v[144:145], v[44:45], v[164:165]
	v_lshlrev_b64 v[164:165], 12, v[172:173]
	v_mul_f32_e32 v144, v144, v168
	v_mul_f32_e32 v145, v145, v163
	v_cvt_pk_bf16_f32 v144, v144, v145
	v_mul_f32_e32 v145, v166, v169
	v_mul_f32_e32 v147, v147, v176
	v_lshl_add_u64 v[164:165], s[12:13], 0, v[164:165]
	v_mul_f32_e32 v163, v167, v174
	v_cvt_pk_bf16_f32 v145, v145, v163
	v_cvt_pk_bf16_f32 v146, v146, v147
	v_mul_f32_e32 v147, v170, v177
	v_lshl_add_u64 v[164:165], v[164:165], 0, v[160:161]
	v_mul_f32_e32 v163, v171, v178
	v_cvt_pk_bf16_f32 v147, v147, v163
	global_store_dwordx4 v[164:165], v[144:147], off offset:2048 sc1
	v_or_b32_e32 v172, 32, v162
	v_ashrrev_i32_e32 v173, 31, v172
	v_mul_f32_e32 v144, 0xbfb8aa3b, v24
	v_mul_f32_e32 v145, 0xbfb8aa3b, v25
	v_exp_f32_e32 v144, v144
	v_exp_f32_e32 v145, v145
	v_mul_f32_e32 v146, 0xbfb8aa3b, v26
	v_mul_f32_e32 v147, 0xbfb8aa3b, v27
	v_exp_f32_e32 v146, v146
	v_exp_f32_e32 v147, v147
	v_add_f32_e32 v144, 1.0, v144
	v_add_f32_e32 v145, 1.0, v145
	v_rcp_f32_e32 v144, v144
	v_rcp_f32_e32 v145, v145
	v_add_f32_e32 v146, 1.0, v146
	v_add_f32_e32 v147, 1.0, v147
	v_rcp_f32_e32 v146, v146
	v_rcp_f32_e32 v147, v147
	v_pk_mul_f32 v[164:165], v[24:25], v[144:145]
	v_mul_f32_e32 v144, 0xbfb8aa3b, v16
	v_mul_f32_e32 v145, 0xbfb8aa3b, v17
	v_exp_f32_e32 v144, v144
	v_exp_f32_e32 v145, v145
	v_pk_mul_f32 v[166:167], v[26:27], v[146:147]
	v_mul_f32_e32 v146, 0xbfb8aa3b, v18
	v_mul_f32_e32 v147, 0xbfb8aa3b, v19
	v_exp_f32_e32 v146, v146
	v_exp_f32_e32 v147, v147
	v_add_f32_e32 v144, 1.0, v144
	v_add_f32_e32 v145, 1.0, v145
	v_rcp_f32_e32 v144, v144
	v_rcp_f32_e32 v145, v145
	v_add_f32_e32 v146, 1.0, v146
	v_add_f32_e32 v147, 1.0, v147
	v_rcp_f32_e32 v146, v146
	v_rcp_f32_e32 v147, v147
	v_pk_mul_f32 v[168:169], v[16:17], v[144:145]
	v_lshlrev_b64 v[144:145], 11, v[172:173]
	v_lshl_add_u64 v[144:145], s[50:51], 0, v[144:145]
	v_lshl_add_u64 v[144:145], v[144:145], 0, v[160:161]
	v_pk_mul_f32 v[170:171], v[18:19], v[146:147]
	s_waitcnt vmcnt(6)
	v_mov_b32_e32 v144, v192
	v_mov_b32_e32 v145, v193
	v_mov_b32_e32 v146, v194
	v_mov_b32_e32 v147, v195
	v_mov_b32_e32 v174, v211
	v_mov_b32_e32 v175, v211
	v_mov_b32_e32 v176, v211
	v_mov_b32_e32 v177, v211
	v_mov_b32_e32 v178, v211
	v_mov_b32_e32 v179, v211
	v_mov_b32_e32 v180, v211
	v_pk_mul_f32 v[166:167], v[30:31], v[166:167]
	v_pk_mul_f32 v[170:171], v[22:23], v[170:171]
	v_cndmask_b32_e64 v163, v144, v148, s[4:5]
	v_cndmask_b32_e64 v148, v148, v144, s[0:1]
	s_nop 0
	v_mov_b32_dpp v174, v163 row_ror:1 row_mask:0xf bank_mask:0xf
	v_mov_b32_e32 v163, v211
	s_nop 1
	v_mov_b32_dpp v163, v148 row_ror:2 row_mask:0xf bank_mask:0xf
	v_cndmask_b32_e64 v148, v145, v149, s[4:5]
	v_cndmask_b32_e64 v149, v149, v145, s[0:1]
	s_nop 0
	v_mov_b32_dpp v175, v148 row_ror:1 row_mask:0xf bank_mask:0xf
	v_mov_b32_dpp v176, v149 row_ror:2 row_mask:0xf bank_mask:0xf
	v_cndmask_b32_e64 v148, v146, v150, s[4:5]
	v_cndmask_b32_e64 v149, v150, v146, s[0:1]
	s_nop 0
	v_mov_b32_dpp v177, v148 row_ror:1 row_mask:0xf bank_mask:0xf
	v_mov_b32_dpp v178, v149 row_ror:2 row_mask:0xf bank_mask:0xf
	v_cndmask_b32_e64 v148, v147, v151, s[4:5]
	v_cndmask_b32_e64 v149, v151, v147, s[0:1]
	v_pk_mul_f32 v[150:151], v[20:21], v[168:169]
	v_mov_b32_dpp v179, v148 row_ror:1 row_mask:0xf bank_mask:0xf
	v_mov_b32_dpp v180, v149 row_ror:2 row_mask:0xf bank_mask:0xf
	v_lshlrev_b32_e32 v149, 16, v174
	v_lshlrev_b32_e32 v148, 16, v144
	v_lshlrev_b32_e32 v168, 16, v163
	v_pk_mul_f32 v[148:149], v[156:157], v[148:149]
	v_and_b32_e32 v163, 0xffff0000, v163
	v_fma_f32 v149, v136, v168, v149
	v_add_f32_e32 v168, v148, v149
	v_and_b32_e32 v149, 0xffff0000, v174
	v_and_b32_e32 v148, 0xffff0000, v144
	v_pk_mul_f32 v[148:149], v[140:141], v[148:149]
	v_lshlrev_b32_e32 v169, 16, v176
	v_fma_f32 v149, v137, v163, v149
	v_add_f32_e32 v163, v148, v149
	v_lshlrev_b32_e32 v149, 16, v175
	v_lshlrev_b32_e32 v148, 16, v145
	v_pk_mul_f32 v[148:149], v[152:153], v[148:149]
	v_and_b32_e32 v174, 0xffff0000, v176
	v_fma_f32 v149, v138, v169, v149
	v_add_f32_e32 v169, v148, v149
	v_and_b32_e32 v149, 0xffff0000, v175
	v_and_b32_e32 v148, 0xffff0000, v145
	v_pk_mul_f32 v[148:149], v[142:143], v[148:149]
	v_lshlrev_b32_e32 v175, 16, v178
	v_fma_f32 v149, v139, v174, v149
	v_add_f32_e32 v174, v148, v149
	v_lshlrev_b32_e32 v149, 16, v177
	v_lshlrev_b32_e32 v148, 16, v146
	v_pk_mul_f32 v[148:149], v[154:155], v[148:149]
	v_and_b32_e32 v176, 0xffff0000, v178
	v_fma_f32 v149, v112, v175, v149
	v_add_f32_e32 v175, v148, v149
	v_and_b32_e32 v149, 0xffff0000, v177
	v_and_b32_e32 v148, 0xffff0000, v146
	v_pk_mul_f32 v[148:149], v[116:117], v[148:149]
	v_lshlrev_b32_e32 v177, 16, v180
	v_fma_f32 v149, v113, v176, v149
	v_add_f32_e32 v176, v148, v149
	v_lshlrev_b32_e32 v149, 16, v179
	v_lshlrev_b32_e32 v148, 16, v147
	v_pk_mul_f32 v[148:149], v[158:159], v[148:149]
	v_and_b32_e32 v178, 0xffff0000, v180
	v_fma_f32 v149, v114, v177, v149
	v_add_f32_e32 v177, v148, v149
	v_and_b32_e32 v149, 0xffff0000, v179
	v_and_b32_e32 v148, 0xffff0000, v147
	v_pk_mul_f32 v[148:149], v[118:119], v[148:149]
	v_mul_f32_e32 v150, v150, v175
	v_fma_f32 v149, v115, v178, v149
	v_add_f32_e32 v178, v148, v149
	v_pk_mul_f32 v[148:149], v[28:29], v[164:165]
	v_mul_f32_e32 v151, v151, v176
	v_mul_f32_e32 v148, v148, v168
	v_mul_f32_e32 v149, v149, v163
	v_or_b32_e32 v168, 48, v162
	v_cvt_pk_bf16_f32 v148, v148, v149
	v_mul_f32_e32 v149, v166, v169
	v_mul_f32_e32 v163, v167, v174
	v_lshlrev_b64 v[164:165], 12, v[172:173]
	v_ashrrev_i32_e32 v169, 31, v168
	v_cvt_pk_bf16_f32 v149, v149, v163
	v_cvt_pk_bf16_f32 v150, v150, v151
	v_mul_f32_e32 v151, v170, v177
	v_mul_f32_e32 v163, v171, v178
	v_lshl_add_u64 v[164:165], s[12:13], 0, v[164:165]
	v_lshlrev_b64 v[170:171], 11, v[168:169]
	v_lshl_add_u64 v[164:165], v[164:165], 0, v[160:161]
	v_lshl_add_u64 v[170:171], s[50:51], 0, v[170:171]
	v_cvt_pk_bf16_f32 v151, v151, v163
	global_store_dwordx4 v[164:165], v[148:151], off offset:2048 sc1
	v_lshl_add_u64 v[170:171], v[170:171], 0, v[160:161]
	s_waitcnt vmcnt(5)
	v_mov_b32_e32 v170, v196
	v_mov_b32_e32 v171, v197
	v_mov_b32_e32 v172, v198
	v_mov_b32_e32 v173, v199
	v_mul_f32_e32 v163, 0xbfb8aa3b, v0
	v_exp_f32_e32 v163, v163
	v_mov_b32_e32 v174, v211
	v_mov_b32_e32 v175, v211
	v_mov_b32_e32 v176, v211
	v_add_f32_e32 v163, 1.0, v163
	v_rcp_f32_e32 v164, v163
	v_mul_f32_e32 v163, 0xbfb8aa3b, v1
	v_exp_f32_e32 v163, v163
	v_mov_b32_e32 v177, v211
	v_mov_b32_e32 v178, v211
	v_mov_b32_e32 v179, v211
	v_add_f32_e32 v163, 1.0, v163
	v_rcp_f32_e32 v165, v163
	v_mul_f32_e32 v163, 0xbfb8aa3b, v2
	v_exp_f32_e32 v163, v163
	v_mov_b32_e32 v180, v211
	v_mul_f32_e32 v148, 0xbfb8aa3b, v8
	v_mul_f32_e32 v149, 0xbfb8aa3b, v9
	v_add_f32_e32 v163, 1.0, v163
	v_rcp_f32_e32 v166, v163
	v_mul_f32_e32 v163, 0xbfb8aa3b, v3
	v_exp_f32_e32 v163, v163
	v_exp_f32_e32 v148, v148
	v_exp_f32_e32 v149, v149
	v_mul_f32_e32 v150, 0xbfb8aa3b, v10
	v_add_f32_e32 v163, 1.0, v163
	v_rcp_f32_e32 v167, v163
	v_mul_f32_e32 v151, 0xbfb8aa3b, v11
	v_exp_f32_e32 v150, v150
	v_exp_f32_e32 v151, v151
	v_add_f32_e32 v148, 1.0, v148
	v_add_f32_e32 v149, 1.0, v149
	v_rcp_f32_e32 v148, v148
	v_rcp_f32_e32 v149, v149
	v_add_f32_e32 v150, 1.0, v150
	v_add_f32_e32 v151, 1.0, v151
	v_rcp_f32_e32 v150, v150
	v_rcp_f32_e32 v151, v151
	v_pk_mul_f32 v[148:149], v[8:9], v[148:149]
	v_pk_mul_f32 v[164:165], v[0:1], v[164:165]
	v_pk_mul_f32 v[166:167], v[2:3], v[166:167]
	v_pk_mul_f32 v[150:151], v[10:11], v[150:151]
	v_pk_mul_f32 v[164:165], v[4:5], v[164:165]
	v_pk_mul_f32 v[166:167], v[6:7], v[166:167]
	v_cndmask_b32_e64 v163, v170, v144, s[4:5]
	v_cndmask_b32_e64 v144, v144, v170, s[0:1]
	s_nop 0
	v_mov_b32_dpp v174, v163 row_ror:1 row_mask:0xf bank_mask:0xf
	v_mov_b32_e32 v163, v211
	s_nop 1
	v_mov_b32_dpp v163, v144 row_ror:2 row_mask:0xf bank_mask:0xf
	v_cndmask_b32_e64 v144, v171, v145, s[4:5]
	v_cndmask_b32_e64 v145, v145, v171, s[0:1]
	v_lshlrev_b32_e32 v181, 16, v163
	v_mov_b32_dpp v175, v144 row_ror:1 row_mask:0xf bank_mask:0xf
	v_mov_b32_dpp v176, v145 row_ror:2 row_mask:0xf bank_mask:0xf
	v_cndmask_b32_e64 v144, v172, v146, s[4:5]
	v_cndmask_b32_e64 v145, v146, v172, s[0:1]
	s_nop 0
	v_mov_b32_dpp v177, v144 row_ror:1 row_mask:0xf bank_mask:0xf
	v_mov_b32_dpp v178, v145 row_ror:2 row_mask:0xf bank_mask:0xf
	v_cndmask_b32_e64 v144, v173, v147, s[4:5]
	v_cndmask_b32_e64 v145, v147, v173, s[0:1]
	s_nop 0
	v_mov_b32_dpp v179, v144 row_ror:1 row_mask:0xf bank_mask:0xf
	v_mov_b32_dpp v180, v145 row_ror:2 row_mask:0xf bank_mask:0xf
	v_lshlrev_b32_e32 v145, 16, v174
	v_lshlrev_b32_e32 v144, 16, v170
	v_pk_mul_f32 v[146:147], v[156:157], v[144:145]
	v_and_b32_e32 v157, 0xffff0000, v174
	v_fma_f32 v136, v136, v181, v147
	v_and_b32_e32 v156, 0xffff0000, v170
	v_add_f32_e32 v145, v146, v136
	v_and_b32_e32 v136, 0xffff0000, v163
	v_pk_mul_f32 v[140:141], v[140:141], v[156:157]
	v_lshlrev_b32_e32 v147, 16, v175
	v_fma_f32 v136, v137, v136, v141
	v_lshlrev_b32_e32 v146, 16, v171
	v_add_f32_e32 v157, v140, v136
	v_lshlrev_b32_e32 v140, 16, v176
	v_pk_mul_f32 v[136:137], v[152:153], v[146:147]
	v_and_b32_e32 v141, 0xffff0000, v175
	v_fma_f32 v137, v138, v140, v137
	v_and_b32_e32 v140, 0xffff0000, v171
	v_add_f32_e32 v147, v136, v137
	v_and_b32_e32 v138, 0xffff0000, v176
	v_pk_mul_f32 v[136:137], v[142:143], v[140:141]
	v_lshlrev_b32_e32 v142, 16, v178
	v_fma_f32 v137, v139, v138, v137
	v_add_f32_e32 v141, v136, v137
	v_lshlrev_b32_e32 v137, 16, v177
	v_lshlrev_b32_e32 v136, 16, v172
	v_pk_mul_f32 v[138:139], v[154:155], v[136:137]
	v_and_b32_e32 v143, 0xffff0000, v177
	v_fma_f32 v112, v112, v142, v139
	v_and_b32_e32 v142, 0xffff0000, v172
	v_add_f32_e32 v137, v138, v112
	v_and_b32_e32 v112, 0xffff0000, v178
	v_pk_mul_f32 v[116:117], v[116:117], v[142:143]
	v_lshlrev_b32_e32 v139, 16, v179
	v_fma_f32 v112, v113, v112, v117
	v_lshlrev_b32_e32 v138, 16, v173
	v_add_f32_e32 v143, v116, v112
	v_lshlrev_b32_e32 v116, 16, v180
	v_pk_mul_f32 v[112:113], v[158:159], v[138:139]
	s_nop 0
	v_fma_f32 v113, v114, v116, v113
	v_add_f32_e32 v139, v112, v113
	v_and_b32_e32 v113, 0xffff0000, v179
	v_and_b32_e32 v112, 0xffff0000, v173
	v_and_b32_e32 v114, 0xffff0000, v180
	v_pk_mul_f32 v[116:117], v[118:119], v[112:113]
	s_nop 0
	v_fma_f32 v113, v115, v114, v117
	v_pk_mul_f32 v[114:115], v[12:13], v[148:149]
	v_add_f32_e32 v118, v116, v113
	v_pk_mul_f32 v[116:117], v[14:15], v[150:151]
	v_mul_f32_e32 v114, v114, v145
	v_mul_f32_e32 v115, v115, v157
	v_cvt_pk_bf16_f32 v114, v114, v115
	v_mul_f32_e32 v115, v116, v147
	v_mul_f32_e32 v116, v117, v141
	v_cvt_pk_bf16_f32 v115, v115, v116
	v_mul_f32_e32 v116, v164, v137
	v_mul_f32_e32 v117, v165, v143
	v_cvt_pk_bf16_f32 v116, v116, v117
	v_mul_f32_e32 v117, v166, v139
	v_mul_f32_e32 v118, v167, v118
	v_cvt_pk_bf16_f32 v117, v117, v118
	v_lshlrev_b64 v[118:119], 12, v[168:169]
	v_bitop3_b32 v113, v162, s8, 48 bitop3:0xc8
	v_lshl_add_u64 v[118:119], s[12:13], 0, v[118:119]
	s_movk_i32 s8, 0x7fd
	v_lshl_add_u64 v[118:119], v[118:119], 0, v[160:161]
	v_cmp_lt_u32_e32 vcc, s8, v113
	global_store_dwordx4 v[118:119], v[114:117], off offset:2048 sc1
	s_and_saveexec_b64 s[8:9], vcc
	s_cbranch_execz .LBB0_320
	v_lshrrev_b32_e32 v114, 21, v169
	v_add_u32_e32 v114, v168, v114
	v_ashrrev_i32_e32 v114, 11, v114
	v_ashrrev_i32_e32 v115, 31, v114
	v_add_u32_e32 v116, 0xfffff802, v113
	v_mov_b32_e32 v117, v211
	v_lshlrev_b64 v[114:115], 13, v[114:115]
	v_lshl_add_u64 v[114:115], s[18:19], 0, v[114:115]
	v_lshlrev_b64 v[116:117], 12, v[116:117]
	v_lshl_add_u64 v[114:115], v[114:115], 0, v[116:117]
	v_lshl_add_u64 v[114:115], v[210:211], 2, v[114:115]
	v_mov_b32_e32 v145, v156
	v_mov_b32_e32 v147, v140
	v_mov_b32_e32 v137, v142
	v_mov_b32_e32 v139, v112
	global_store_dwordx4 v[114:115], v[144:147], off
	global_store_dwordx4 v[114:115], v[136:139], off offset:16

.LBB0_338:
	v_add_u32_e32 v128, s87, v234
	v_ashrrev_i32_e32 v129, 31, v128
	v_lshl_add_u64 v[168:169], v[128:129], 2, s[56:57]
	global_load_dword v130, v[168:169], off
	v_lshlrev_b32_e32 v131, 16, v127
	v_and_b32_e32 v127, 0xffff0000, v127
	v_lshlrev_b32_e32 v132, 16, v126
	v_and_b32_e32 v126, 0xffff0000, v126
	v_lshlrev_b32_e32 v133, 16, v125
	v_and_b32_e32 v125, 0xffff0000, v125
	v_lshlrev_b32_e32 v134, 16, v124
	v_and_b32_e32 v124, 0xffff0000, v124
	v_add_u32_e32 v171, s99, v212
	v_add_u32_e32 v128, s94, v234
	v_ashrrev_i32_e32 v129, 31, v128
	s_and_b64 vcc, exec, s[8:9]
	s_waitcnt vmcnt(0)
	v_fma_f32 v64, v116, v64, v130
	v_fma_f32 v65, v117, v65, v130
	v_fma_f32 v66, v118, v66, v130
	v_fma_f32 v67, v119, v67, v130
	v_fma_f32 v68, v112, v68, v130
	v_fma_f32 v69, v113, v69, v130
	v_fma_f32 v70, v114, v70, v130
	v_fmac_f32_e32 v130, v115, v71
	v_mul_f32_e32 v64, v64, v131
	v_mul_f32_e32 v65, v65, v127
	v_mul_f32_e32 v66, v66, v132
	v_mul_f32_e32 v67, v67, v126
	v_mul_f32_e32 v68, v68, v133
	v_mul_f32_e32 v69, v69, v125
	v_mul_f32_e32 v70, v70, v134
	v_mul_f32_e32 v71, v130, v124
	v_cvt_pk_bf16_f32 v64, v64, v65
	v_cvt_pk_bf16_f32 v65, v66, v67
	v_cvt_pk_bf16_f32 v66, v68, v69
	v_cvt_pk_bf16_f32 v67, v70, v71
	ds_read_b128 v[68:71], v171 offset:256
	v_lshlrev_b64 v[124:125], 12, v[128:129]
	v_lshl_add_u64 v[124:125], s[12:13], 0, v[124:125]
	v_lshl_add_u64 v[124:125], v[228:229], 1, v[124:125]
	global_store_dwordx4 v[124:125], v[64:67], off sc1
	s_waitcnt lgkmcnt(0)
	s_nop 0
	v_lshlrev_b32_e32 v64, 16, v68
	v_and_b32_e32 v65, 0xffff0000, v68
	v_lshlrev_b32_e32 v66, 16, v69
	v_and_b32_e32 v67, 0xffff0000, v69
	v_lshlrev_b32_e32 v68, 16, v70
	v_and_b32_e32 v69, 0xffff0000, v70
	v_lshlrev_b32_e32 v70, 16, v71
	v_and_b32_e32 v71, 0xffff0000, v71
	v_mul_f32_e32 v64, v88, v64
	v_mul_f32_e32 v65, v90, v65
	v_mul_f32_e32 v66, v92, v66
	v_mul_f32_e32 v67, v94, v67
	v_mul_f32_e32 v68, v87, v68
	v_mul_f32_e32 v69, v89, v69
	v_mul_f32_e32 v70, v91, v70
	v_mul_f32_e32 v71, v93, v71
	v_cvt_pk_bf16_f32 v64, v64, v65
	v_cvt_pk_bf16_f32 v65, v66, v67
	v_cvt_pk_bf16_f32 v66, v68, v69
	v_cvt_pk_bf16_f32 v67, v70, v71
	s_nop 0
	v_mfma_f32_16x16x32_bf16 v[68:71], v[164:167], v[64:67], 0
	v_mfma_f32_16x16x32_bf16 v[64:67], v[160:163], v[64:67], 0
	s_cbranch_vccz .LBB0_353
	s_and_b64 vcc, exec, s[8:9]
	s_cbranch_vccz .LBB0_354

.LBB0_342:
	global_load_dword v125, v[168:169], off offset:64
	v_lshlrev_b32_e32 v126, 16, v123
	v_and_b32_e32 v123, 0xffff0000, v123
	v_add_u32_e32 v124, s94, v240
	v_add_u32_e32 v170, s43, v212
	s_and_b64 vcc, exec, s[8:9]
	s_waitcnt vmcnt(0)
	v_fma_f32 v68, v116, v68, v125
	v_fma_f32 v69, v117, v69, v125
	v_mul_f32_e32 v68, v68, v126
	v_mul_f32_e32 v69, v69, v123
	v_cvt_pk_bf16_f32 v68, v68, v69
	v_lshlrev_b32_e32 v69, 16, v122
	v_fma_f32 v70, v118, v70, v125
	v_mul_f32_e32 v69, v70, v69
	v_and_b32_e32 v70, 0xffff0000, v122
	v_fma_f32 v71, v119, v71, v125
	v_mul_f32_e32 v70, v71, v70
	v_cvt_pk_bf16_f32 v69, v69, v70
	v_lshlrev_b32_e32 v70, 16, v121
	v_fma_f32 v64, v112, v64, v125
	v_mul_f32_e32 v64, v64, v70
	v_and_b32_e32 v70, 0xffff0000, v121
	v_fma_f32 v65, v113, v65, v125
	v_mul_f32_e32 v65, v65, v70
	v_cvt_pk_bf16_f32 v70, v64, v65
	v_lshlrev_b32_e32 v64, 16, v120
	v_fma_f32 v65, v114, v66, v125
	v_mul_f32_e32 v64, v65, v64
	v_and_b32_e32 v65, 0xffff0000, v120
	v_fmac_f32_e32 v125, v115, v67
	v_mul_f32_e32 v65, v125, v65
	v_ashrrev_i32_e32 v125, 31, v124
	v_cvt_pk_bf16_f32 v71, v64, v65
	v_lshlrev_b64 v[64:65], 12, v[124:125]
	v_lshl_add_u64 v[64:65], s[12:13], 0, v[64:65]
	v_lshl_add_u64 v[64:65], v[228:229], 1, v[64:65]
	global_store_dwordx4 v[64:65], v[68:71], off sc1
	ds_read_b128 v[64:67], v170
	s_waitcnt lgkmcnt(0)
	v_lshlrev_b32_e32 v68, 16, v64
	v_and_b32_e32 v64, 0xffff0000, v64
	v_mul_f32_e32 v68, v88, v68
	v_mul_f32_e32 v64, v90, v64
	v_cvt_pk_bf16_f32 v64, v68, v64
	v_lshlrev_b32_e32 v68, 16, v65
	v_and_b32_e32 v65, 0xffff0000, v65
	v_mul_f32_e32 v68, v92, v68
	v_mul_f32_e32 v65, v94, v65
	v_cvt_pk_bf16_f32 v65, v68, v65
	v_lshlrev_b32_e32 v68, 16, v66
	v_and_b32_e32 v66, 0xffff0000, v66
	v_mul_f32_e32 v68, v87, v68
	v_mul_f32_e32 v66, v89, v66
	v_cvt_pk_bf16_f32 v66, v68, v66
	v_lshlrev_b32_e32 v68, 16, v67
	v_and_b32_e32 v67, 0xffff0000, v67
	v_mul_f32_e32 v67, v93, v67
	v_mul_f32_e32 v68, v91, v68
	v_cvt_pk_bf16_f32 v67, v68, v67
	ds_read_b128 v[120:123], v170 offset:1024
	v_mfma_f32_16x16x32_bf16 v[68:71], v[164:167], v[64:67], 0
	s_waitcnt lgkmcnt(0)
	v_lshlrev_b32_e32 v124, 16, v120
	v_and_b32_e32 v120, 0xffff0000, v120
	v_mul_f32_e32 v124, v77, v124
	v_mul_f32_e32 v120, v79, v120
	v_cvt_pk_bf16_f32 v120, v124, v120
	v_lshlrev_b32_e32 v124, 16, v121
	v_and_b32_e32 v121, 0xffff0000, v121
	v_mul_f32_e32 v124, v84, v124
	v_mul_f32_e32 v121, v86, v121
	v_mfma_f32_16x16x32_bf16 v[64:67], v[160:163], v[64:67], 0
	v_cvt_pk_bf16_f32 v121, v124, v121
	v_lshlrev_b32_e32 v124, 16, v122
	v_and_b32_e32 v122, 0xffff0000, v122
	v_mul_f32_e32 v124, v76, v124
	v_mul_f32_e32 v122, v78, v122
	v_cvt_pk_bf16_f32 v122, v124, v122
	v_lshlrev_b32_e32 v124, 16, v123
	v_and_b32_e32 v123, 0xffff0000, v123
	v_mul_f32_e32 v123, v95, v123
	v_mul_f32_e32 v124, v85, v124
	v_cvt_pk_bf16_f32 v123, v124, v123
	s_nop 0
	v_mfma_f32_16x16x32_bf16 v[68:71], v[148:151], v[120:123], v[68:71]
	v_mfma_f32_16x16x32_bf16 v[64:67], v[144:147], v[120:123], v[64:67]
	s_cbranch_vccnz .LBB0_344
	ds_read_b128 v[120:123], v170 offset:2048
	s_waitcnt lgkmcnt(0)
	v_lshlrev_b32_e32 v124, 16, v120
	v_and_b32_e32 v120, 0xffff0000, v120
	v_mul_f32_e32 v124, v103, v124
	v_mul_f32_e32 v120, v102, v120
	v_cvt_pk_bf16_f32 v120, v124, v120
	v_lshlrev_b32_e32 v124, 16, v121
	v_and_b32_e32 v121, 0xffff0000, v121
	v_mul_f32_e32 v124, v101, v124
	v_mul_f32_e32 v121, v100, v121
	v_cvt_pk_bf16_f32 v121, v124, v121
	v_lshlrev_b32_e32 v124, 16, v122
	v_and_b32_e32 v122, 0xffff0000, v122
	v_mul_f32_e32 v124, v96, v124
	v_mul_f32_e32 v122, v97, v122
	v_cvt_pk_bf16_f32 v122, v124, v122
	v_lshlrev_b32_e32 v124, 16, v123
	v_and_b32_e32 v123, 0xffff0000, v123
	v_mul_f32_e32 v123, v99, v123
	v_mul_f32_e32 v124, v98, v124
	v_cvt_pk_bf16_f32 v123, v124, v123
	s_nop 0
	v_mfma_f32_16x16x32_bf16 v[68:71], v[140:143], v[120:123], v[68:71]
	v_mfma_f32_16x16x32_bf16 v[64:67], v[136:139], v[120:123], v[64:67]

.LBB0_346:
	global_load_dword v122, v[168:169], off offset:128
	v_lshlrev_b32_e32 v123, 16, v83
	v_and_b32_e32 v83, 0xffff0000, v83
	v_lshlrev_b32_e32 v124, 16, v82
	v_and_b32_e32 v82, 0xffff0000, v82
	v_lshlrev_b32_e32 v125, 16, v81
	v_and_b32_e32 v81, 0xffff0000, v81
	v_lshlrev_b32_e32 v126, 16, v80
	v_and_b32_e32 v80, 0xffff0000, v80
	v_add_u32_e32 v172, s75, v212
	v_add_u32_e32 v120, s94, v241
	v_ashrrev_i32_e32 v121, 31, v120
	s_and_b64 vcc, exec, s[8:9]
	s_waitcnt vmcnt(0)
	v_fma_f32 v68, v116, v68, v122
	v_fma_f32 v69, v117, v69, v122
	v_fma_f32 v70, v118, v70, v122
	v_fma_f32 v71, v119, v71, v122
	v_fma_f32 v64, v112, v64, v122
	v_fma_f32 v65, v113, v65, v122
	v_fma_f32 v66, v114, v66, v122
	v_fmac_f32_e32 v122, v115, v67
	v_mul_f32_e32 v67, v68, v123
	v_mul_f32_e32 v68, v69, v83
	v_mul_f32_e32 v69, v70, v124
	v_mul_f32_e32 v70, v71, v82
	v_mul_f32_e32 v71, v64, v125
	v_mul_f32_e32 v81, v65, v81
	v_mul_f32_e32 v82, v66, v126
	v_mul_f32_e32 v80, v122, v80
	v_cvt_pk_bf16_f32 v64, v67, v68
	v_cvt_pk_bf16_f32 v65, v69, v70
	v_cvt_pk_bf16_f32 v66, v71, v81
	v_cvt_pk_bf16_f32 v67, v82, v80
	ds_read_b128 v[68:71], v172 offset:256
	v_lshlrev_b64 v[80:81], 12, v[120:121]
	v_lshl_add_u64 v[80:81], s[12:13], 0, v[80:81]
	v_lshl_add_u64 v[80:81], v[228:229], 1, v[80:81]
	global_store_dwordx4 v[80:81], v[64:67], off sc1
	s_waitcnt lgkmcnt(0)
	s_nop 0
	v_lshlrev_b32_e32 v64, 16, v68
	v_and_b32_e32 v65, 0xffff0000, v68
	v_lshlrev_b32_e32 v66, 16, v69
	v_and_b32_e32 v67, 0xffff0000, v69
	v_lshlrev_b32_e32 v68, 16, v70
	v_and_b32_e32 v69, 0xffff0000, v70
	v_lshlrev_b32_e32 v70, 16, v71
	v_and_b32_e32 v71, 0xffff0000, v71
	v_mul_f32_e32 v64, v88, v64
	v_mul_f32_e32 v65, v90, v65
	v_mul_f32_e32 v66, v92, v66
	v_mul_f32_e32 v67, v94, v67
	v_mul_f32_e32 v68, v87, v68
	v_mul_f32_e32 v69, v89, v69
	v_mul_f32_e32 v70, v91, v70
	v_mul_f32_e32 v71, v93, v71
	v_cvt_pk_bf16_f32 v64, v64, v65
	v_cvt_pk_bf16_f32 v65, v66, v67
	v_cvt_pk_bf16_f32 v66, v68, v69
	v_cvt_pk_bf16_f32 v67, v70, v71
	ds_read_b128 v[80:83], v172 offset:1280
	v_mfma_f32_16x16x32_bf16 v[68:71], v[164:167], v[64:67], 0
	s_waitcnt lgkmcnt(0)
	v_lshlrev_b32_e32 v87, 16, v80
	v_mfma_f32_16x16x32_bf16 v[64:67], v[160:163], v[64:67], 0
	v_and_b32_e32 v80, 0xffff0000, v80
	v_lshlrev_b32_e32 v89, 16, v82
	v_and_b32_e32 v82, 0xffff0000, v82
	v_lshlrev_b32_e32 v88, 16, v81
	v_and_b32_e32 v81, 0xffff0000, v81
	v_lshlrev_b32_e32 v90, 16, v83
	v_and_b32_e32 v83, 0xffff0000, v83
	v_mul_f32_e32 v77, v77, v87
	v_mul_f32_e32 v79, v79, v80
	v_mul_f32_e32 v78, v78, v82
	v_mul_f32_e32 v80, v84, v88
	v_mul_f32_e32 v81, v86, v81
	v_mul_f32_e32 v84, v76, v89
	v_mul_f32_e32 v82, v85, v90
	v_mul_f32_e32 v83, v95, v83
	v_cvt_pk_bf16_f32 v76, v77, v79
	v_cvt_pk_bf16_f32 v77, v80, v81
	v_cvt_pk_bf16_f32 v78, v84, v78
	v_cvt_pk_bf16_f32 v79, v82, v83
	s_nop 0
	v_mfma_f32_16x16x32_bf16 v[68:71], v[148:151], v[76:79], v[68:71]
	v_mfma_f32_16x16x32_bf16 v[64:67], v[144:147], v[76:79], v[64:67]
	s_cbranch_vccnz .LBB0_348
	ds_read_b128 v[76:79], v172 offset:2304
	s_waitcnt lgkmcnt(0)
	v_lshlrev_b32_e32 v80, 16, v76
	v_and_b32_e32 v76, 0xffff0000, v76
	v_mul_f32_e32 v80, v103, v80
	v_mul_f32_e32 v76, v102, v76
	v_cvt_pk_bf16_f32 v76, v80, v76
	v_lshlrev_b32_e32 v80, 16, v77
	v_and_b32_e32 v77, 0xffff0000, v77
	v_mul_f32_e32 v80, v101, v80
	v_mul_f32_e32 v77, v100, v77
	v_cvt_pk_bf16_f32 v77, v80, v77
	v_lshlrev_b32_e32 v80, 16, v78
	v_and_b32_e32 v78, 0xffff0000, v78
	v_mul_f32_e32 v80, v96, v80
	v_mul_f32_e32 v78, v97, v78
	v_cvt_pk_bf16_f32 v78, v80, v78
	v_lshlrev_b32_e32 v80, 16, v79
	v_and_b32_e32 v79, 0xffff0000, v79
	v_mul_f32_e32 v79, v99, v79
	v_mul_f32_e32 v80, v98, v80
	v_cvt_pk_bf16_f32 v79, v80, v79
	s_nop 0
	v_mfma_f32_16x16x32_bf16 v[68:71], v[140:143], v[76:79], v[68:71]
	v_mfma_f32_16x16x32_bf16 v[64:67], v[136:139], v[76:79], v[64:67]

.LBB0_350:
	global_load_dword v77, v[168:169], off offset:192
	v_lshlrev_b32_e32 v78, 16, v75
	v_and_b32_e32 v75, 0xffff0000, v75
	v_add_u32_e32 v76, s94, v242
	s_or_b32 s16, s72, 1
	s_ashr_i32 s17, s16, 31
	s_lshl_b32 s26, s16, 7
	s_lshl_b64 s[16:17], s[16:17], 18
	s_ashr_i32 s27, s26, 31
	v_lshl_add_u64 v[88:89], s[26:27], 2, v[214:215]
	v_mov_b32_e32 v96, 0
	s_waitcnt vmcnt(0)
	v_fma_f32 v68, v116, v68, v77
	v_fma_f32 v69, v117, v69, v77
	v_mul_f32_e32 v68, v68, v78
	v_mul_f32_e32 v69, v69, v75
	v_cvt_pk_bf16_f32 v68, v68, v69
	v_lshlrev_b32_e32 v69, 16, v74
	v_fma_f32 v70, v118, v70, v77
	v_mul_f32_e32 v69, v70, v69
	v_and_b32_e32 v70, 0xffff0000, v74
	v_fma_f32 v71, v119, v71, v77
	v_mul_f32_e32 v70, v71, v70
	v_cvt_pk_bf16_f32 v69, v69, v70
	v_lshlrev_b32_e32 v70, 16, v73
	v_fma_f32 v64, v112, v64, v77
	v_mul_f32_e32 v64, v64, v70
	v_and_b32_e32 v70, 0xffff0000, v73
	v_fma_f32 v65, v113, v65, v77
	v_mul_f32_e32 v65, v65, v70
	v_cvt_pk_bf16_f32 v70, v64, v65
	v_lshlrev_b32_e32 v64, 16, v72
	v_fma_f32 v65, v114, v66, v77
	v_mul_f32_e32 v64, v65, v64
	v_and_b32_e32 v65, 0xffff0000, v72
	v_fmac_f32_e32 v77, v115, v67
	v_mul_f32_e32 v65, v77, v65
	v_ashrrev_i32_e32 v77, 31, v76
	v_cvt_pk_bf16_f32 v71, v64, v65
	v_lshlrev_b64 v[64:65], 12, v[76:77]
	v_lshl_add_u64 v[64:65], s[12:13], 0, v[64:65]
	v_lshl_add_u64 v[64:65], v[228:229], 1, v[64:65]
	global_store_dwordx4 v[64:65], v[68:71], off sc1
	v_lshl_add_u64 v[64:65], v[216:217], 0, s[16:17]
	v_lshl_add_u64 v[90:91], v[64:65], 0, s[40:41]
	v_add_co_u32_e32 v72, vcc, 0x1000, v90
	global_load_dwordx4 v[100:103], v[88:89], off offset:16
	global_load_dwordx4 v[104:107], v[88:89], off
	v_addc_co_u32_e32 v73, vcc, 0, v91, vcc
	global_load_dwordx4 v[64:67], v[90:91], off nt
	global_load_dwordx4 v[68:71], v[72:73], off nt
	global_load_dwordx4 v[128:131], v[88:89], off offset:144
	global_load_dwordx4 v[132:135], v[88:89], off offset:128
	global_load_dwordx4 v[80:83], v[90:91], off offset:1024 nt
	global_load_dwordx4 v[84:87], v[72:73], off offset:1024 nt
	s_and_b64 vcc, exec, s[8:9]
	s_cbranch_vccnz .LBB0_355
	v_add_co_u32_e32 v72, vcc, 0x1000, v90
	global_load_dwordx4 v[108:111], v[88:89], off offset:256
	global_load_dwordx4 v[124:127], v[88:89], off offset:272
	v_addc_co_u32_e32 v73, vcc, 0, v91, vcc
	global_load_dwordx4 v[76:79], v[90:91], off offset:2048 nt
	s_nop 0
	global_load_dwordx4 v[72:75], v[72:73], off offset:2048 nt
	s_and_b64 vcc, exec, s[8:9]
	s_cbranch_vccz .LBB0_356

.LBB0_363:
	global_load_dword v56, v[168:169], off
	v_lshlrev_b32_e32 v57, 16, v55
	v_and_b32_e32 v55, 0xffff0000, v55
	v_lshlrev_b32_e32 v58, 16, v54
	v_and_b32_e32 v54, 0xffff0000, v54
	v_lshlrev_b32_e32 v59, 16, v53
	v_and_b32_e32 v60, 0xffff0000, v53
	v_lshlrev_b32_e32 v61, 16, v52
	v_and_b32_e32 v62, 0xffff0000, v52
	s_or_b32 s40, s94, 0x80
	v_add_u32_e32 v52, s40, v234
	v_ashrrev_i32_e32 v53, 31, v52
	v_lshlrev_b64 v[52:53], 12, v[52:53]
	v_lshl_add_u64 v[52:53], s[12:13], 0, v[52:53]
	v_lshl_add_u64 v[52:53], v[228:229], 1, v[52:53]
	s_and_b64 vcc, exec, s[8:9]
	s_waitcnt vmcnt(0)
	v_fma_f32 v0, v116, v0, v56
	v_fma_f32 v1, v117, v1, v56
	v_fma_f32 v2, v118, v2, v56
	v_fma_f32 v3, v119, v3, v56
	v_fma_f32 v4, v112, v4, v56
	v_fma_f32 v5, v113, v5, v56
	v_fma_f32 v6, v114, v6, v56
	v_fmac_f32_e32 v56, v115, v7
	v_mul_f32_e32 v0, v0, v57
	v_mul_f32_e32 v1, v1, v55
	v_mul_f32_e32 v2, v2, v58
	v_mul_f32_e32 v3, v3, v54
	v_mul_f32_e32 v4, v4, v59
	v_mul_f32_e32 v5, v5, v60
	v_mul_f32_e32 v6, v6, v61
	v_mul_f32_e32 v7, v56, v62
	v_cvt_pk_bf16_f32 v0, v0, v1
	v_cvt_pk_bf16_f32 v1, v2, v3
	v_cvt_pk_bf16_f32 v2, v4, v5
	v_cvt_pk_bf16_f32 v3, v6, v7
	ds_read_b128 v[4:7], v171 offset:256
	global_store_dwordx4 v[52:53], v[0:3], off sc1
	s_waitcnt lgkmcnt(0)
	s_nop 0
	v_lshlrev_b32_e32 v0, 16, v4
	v_and_b32_e32 v1, 0xffff0000, v4
	v_lshlrev_b32_e32 v2, 16, v5
	v_and_b32_e32 v3, 0xffff0000, v5
	v_lshlrev_b32_e32 v4, 16, v6
	v_and_b32_e32 v5, 0xffff0000, v6
	v_lshlrev_b32_e32 v6, 16, v7
	v_and_b32_e32 v7, 0xffff0000, v7
	v_mul_f32_e32 v0, v24, v0
	v_mul_f32_e32 v1, v26, v1
	v_mul_f32_e32 v2, v28, v2
	v_mul_f32_e32 v3, v30, v3
	v_mul_f32_e32 v4, v23, v4
	v_mul_f32_e32 v5, v25, v5
	v_mul_f32_e32 v6, v27, v6
	v_mul_f32_e32 v7, v29, v7
	v_cvt_pk_bf16_f32 v0, v0, v1
	v_cvt_pk_bf16_f32 v1, v2, v3
	v_cvt_pk_bf16_f32 v2, v4, v5
	v_cvt_pk_bf16_f32 v3, v6, v7
	s_nop 0
	v_mfma_f32_16x16x32_bf16 v[4:7], v[64:67], v[0:3], 0
	v_mfma_f32_16x16x32_bf16 v[0:3], v[68:71], v[0:3], 0
	s_cbranch_vccz .LBB0_378
	s_and_b64 vcc, exec, s[8:9]
	s_cbranch_vccz .LBB0_379

.LBB0_367:
	global_load_dword v53, v[168:169], off offset:64
	v_lshlrev_b32_e32 v54, 16, v51
	v_and_b32_e32 v51, 0xffff0000, v51
	v_add_u32_e32 v52, s40, v240
	s_and_b64 vcc, exec, s[8:9]
	s_waitcnt vmcnt(0)
	s_nop 0
	v_fma_f32 v4, v116, v4, v53
	v_fma_f32 v5, v117, v5, v53
	v_mul_f32_e32 v4, v4, v54
	v_mul_f32_e32 v5, v5, v51
	v_cvt_pk_bf16_f32 v4, v4, v5
	v_lshlrev_b32_e32 v5, 16, v50
	v_fma_f32 v6, v118, v6, v53
	v_mul_f32_e32 v5, v6, v5
	v_and_b32_e32 v6, 0xffff0000, v50
	v_fma_f32 v7, v119, v7, v53
	v_mul_f32_e32 v6, v7, v6
	v_cvt_pk_bf16_f32 v5, v5, v6
	v_lshlrev_b32_e32 v6, 16, v49
	v_fma_f32 v0, v112, v0, v53
	v_mul_f32_e32 v0, v0, v6
	v_and_b32_e32 v6, 0xffff0000, v49
	v_fma_f32 v1, v113, v1, v53
	v_mul_f32_e32 v1, v1, v6
	v_cvt_pk_bf16_f32 v6, v0, v1
	v_lshlrev_b32_e32 v0, 16, v48
	v_fma_f32 v1, v114, v2, v53
	v_mul_f32_e32 v0, v1, v0
	v_and_b32_e32 v1, 0xffff0000, v48
	v_fmac_f32_e32 v53, v115, v3
	v_mul_f32_e32 v1, v53, v1
	v_ashrrev_i32_e32 v53, 31, v52
	v_cvt_pk_bf16_f32 v7, v0, v1
	v_lshlrev_b64 v[0:1], 12, v[52:53]
	v_lshl_add_u64 v[0:1], s[12:13], 0, v[0:1]
	v_lshl_add_u64 v[0:1], v[228:229], 1, v[0:1]
	global_store_dwordx4 v[0:1], v[4:7], off sc1
	ds_read_b128 v[0:3], v170
	s_waitcnt lgkmcnt(0)
	v_lshlrev_b32_e32 v4, 16, v0
	v_and_b32_e32 v0, 0xffff0000, v0
	v_mul_f32_e32 v4, v24, v4
	v_mul_f32_e32 v0, v26, v0
	v_cvt_pk_bf16_f32 v0, v4, v0
	v_lshlrev_b32_e32 v4, 16, v1
	v_and_b32_e32 v1, 0xffff0000, v1
	v_mul_f32_e32 v4, v28, v4
	v_mul_f32_e32 v1, v30, v1
	v_cvt_pk_bf16_f32 v1, v4, v1
	v_lshlrev_b32_e32 v4, 16, v2
	v_and_b32_e32 v2, 0xffff0000, v2
	v_mul_f32_e32 v4, v23, v4
	v_mul_f32_e32 v2, v25, v2
	v_cvt_pk_bf16_f32 v2, v4, v2
	v_lshlrev_b32_e32 v4, 16, v3
	v_and_b32_e32 v3, 0xffff0000, v3
	v_mul_f32_e32 v3, v29, v3
	v_mul_f32_e32 v4, v27, v4
	v_cvt_pk_bf16_f32 v3, v4, v3
	ds_read_b128 v[48:51], v170 offset:1024
	v_mfma_f32_16x16x32_bf16 v[4:7], v[64:67], v[0:3], 0
	s_waitcnt lgkmcnt(0)
	v_lshlrev_b32_e32 v52, 16, v48
	v_and_b32_e32 v48, 0xffff0000, v48
	v_mul_f32_e32 v52, v13, v52
	v_mul_f32_e32 v48, v15, v48
	v_cvt_pk_bf16_f32 v48, v52, v48
	v_lshlrev_b32_e32 v52, 16, v49
	v_and_b32_e32 v49, 0xffff0000, v49
	v_mul_f32_e32 v52, v20, v52
	v_mul_f32_e32 v49, v22, v49
	v_mfma_f32_16x16x32_bf16 v[0:3], v[68:71], v[0:3], 0
	v_cvt_pk_bf16_f32 v49, v52, v49
	v_lshlrev_b32_e32 v52, 16, v50
	v_and_b32_e32 v50, 0xffff0000, v50
	v_mul_f32_e32 v52, v12, v52
	v_mul_f32_e32 v50, v14, v50
	v_cvt_pk_bf16_f32 v50, v52, v50
	v_lshlrev_b32_e32 v52, 16, v51
	v_and_b32_e32 v51, 0xffff0000, v51
	v_mul_f32_e32 v51, v31, v51
	v_mul_f32_e32 v52, v21, v52
	v_cvt_pk_bf16_f32 v51, v52, v51
	s_nop 0
	v_mfma_f32_16x16x32_bf16 v[4:7], v[80:83], v[48:51], v[4:7]
	v_mfma_f32_16x16x32_bf16 v[0:3], v[84:87], v[48:51], v[0:3]
	s_cbranch_vccnz .LBB0_369
	ds_read_b128 v[48:51], v170 offset:2048
	s_waitcnt lgkmcnt(0)
	v_lshlrev_b32_e32 v52, 16, v48
	v_and_b32_e32 v48, 0xffff0000, v48
	v_mul_f32_e32 v52, v39, v52
	v_mul_f32_e32 v48, v38, v48
	v_cvt_pk_bf16_f32 v48, v52, v48
	v_lshlrev_b32_e32 v52, 16, v49
	v_and_b32_e32 v49, 0xffff0000, v49
	v_mul_f32_e32 v52, v37, v52
	v_mul_f32_e32 v49, v36, v49
	v_cvt_pk_bf16_f32 v49, v52, v49
	v_lshlrev_b32_e32 v52, 16, v50
	v_and_b32_e32 v50, 0xffff0000, v50
	v_mul_f32_e32 v52, v32, v52
	v_mul_f32_e32 v50, v33, v50
	v_cvt_pk_bf16_f32 v50, v52, v50
	v_lshlrev_b32_e32 v52, 16, v51
	v_and_b32_e32 v51, 0xffff0000, v51
	v_mul_f32_e32 v51, v35, v51
	v_mul_f32_e32 v52, v34, v52
	v_cvt_pk_bf16_f32 v51, v52, v51
	s_nop 0
	v_mfma_f32_16x16x32_bf16 v[4:7], v[76:79], v[48:51], v[4:7]
	v_mfma_f32_16x16x32_bf16 v[0:3], v[72:75], v[48:51], v[0:3]

.LBB0_371:
	global_load_dword v50, v[168:169], off offset:128
	v_lshlrev_b32_e32 v51, 16, v19
	v_and_b32_e32 v19, 0xffff0000, v19
	v_lshlrev_b32_e32 v52, 16, v18
	v_and_b32_e32 v18, 0xffff0000, v18
	v_lshlrev_b32_e32 v53, 16, v17
	v_and_b32_e32 v17, 0xffff0000, v17
	v_lshlrev_b32_e32 v54, 16, v16
	v_and_b32_e32 v16, 0xffff0000, v16
	v_add_u32_e32 v48, s40, v241
	v_ashrrev_i32_e32 v49, 31, v48
	s_and_b64 vcc, exec, s[8:9]
	s_waitcnt vmcnt(0)
	v_fma_f32 v4, v116, v4, v50
	v_fma_f32 v5, v117, v5, v50
	v_fma_f32 v6, v118, v6, v50
	v_fma_f32 v7, v119, v7, v50
	v_fma_f32 v0, v112, v0, v50
	v_fma_f32 v1, v113, v1, v50
	v_fma_f32 v2, v114, v2, v50
	v_fmac_f32_e32 v50, v115, v3
	v_mul_f32_e32 v3, v4, v51
	v_mul_f32_e32 v4, v5, v19
	v_mul_f32_e32 v5, v6, v52
	v_mul_f32_e32 v6, v7, v18
	v_mul_f32_e32 v7, v0, v53
	v_mul_f32_e32 v17, v1, v17
	v_mul_f32_e32 v18, v2, v54
	v_mul_f32_e32 v16, v50, v16
	v_cvt_pk_bf16_f32 v0, v3, v4
	v_cvt_pk_bf16_f32 v1, v5, v6
	v_cvt_pk_bf16_f32 v2, v7, v17
	v_cvt_pk_bf16_f32 v3, v18, v16
	ds_read_b128 v[4:7], v172 offset:256
	v_lshlrev_b64 v[16:17], 12, v[48:49]
	v_lshl_add_u64 v[16:17], s[12:13], 0, v[16:17]
	v_lshl_add_u64 v[16:17], v[228:229], 1, v[16:17]
	global_store_dwordx4 v[16:17], v[0:3], off sc1
	s_waitcnt lgkmcnt(0)
	s_nop 0
	v_lshlrev_b32_e32 v0, 16, v4
	v_and_b32_e32 v1, 0xffff0000, v4
	v_lshlrev_b32_e32 v2, 16, v5
	v_and_b32_e32 v3, 0xffff0000, v5
	v_lshlrev_b32_e32 v4, 16, v6
	v_and_b32_e32 v5, 0xffff0000, v6
	v_lshlrev_b32_e32 v6, 16, v7
	v_and_b32_e32 v7, 0xffff0000, v7
	v_mul_f32_e32 v0, v24, v0
	v_mul_f32_e32 v1, v26, v1
	v_mul_f32_e32 v2, v28, v2
	v_mul_f32_e32 v3, v30, v3
	v_mul_f32_e32 v4, v23, v4
	v_mul_f32_e32 v5, v25, v5
	v_mul_f32_e32 v6, v27, v6
	v_mul_f32_e32 v7, v29, v7
	v_cvt_pk_bf16_f32 v0, v0, v1
	v_cvt_pk_bf16_f32 v1, v2, v3
	v_cvt_pk_bf16_f32 v2, v4, v5
	v_cvt_pk_bf16_f32 v3, v6, v7
	ds_read_b128 v[16:19], v172 offset:1280
	v_mfma_f32_16x16x32_bf16 v[4:7], v[64:67], v[0:3], 0
	s_waitcnt lgkmcnt(0)
	v_lshlrev_b32_e32 v23, 16, v16
	v_mfma_f32_16x16x32_bf16 v[0:3], v[68:71], v[0:3], 0
	v_and_b32_e32 v16, 0xffff0000, v16
	v_lshlrev_b32_e32 v25, 16, v18
	v_and_b32_e32 v18, 0xffff0000, v18
	v_lshlrev_b32_e32 v24, 16, v17
	v_and_b32_e32 v17, 0xffff0000, v17
	v_lshlrev_b32_e32 v26, 16, v19
	v_and_b32_e32 v19, 0xffff0000, v19
	v_mul_f32_e32 v13, v13, v23
	v_mul_f32_e32 v15, v15, v16
	v_mul_f32_e32 v14, v14, v18
	v_mul_f32_e32 v16, v20, v24
	v_mul_f32_e32 v17, v22, v17
	v_mul_f32_e32 v20, v12, v25
	v_mul_f32_e32 v18, v21, v26
	v_mul_f32_e32 v19, v31, v19
	v_cvt_pk_bf16_f32 v12, v13, v15
	v_cvt_pk_bf16_f32 v13, v16, v17
	v_cvt_pk_bf16_f32 v14, v20, v14
	v_cvt_pk_bf16_f32 v15, v18, v19
	s_nop 0
	v_mfma_f32_16x16x32_bf16 v[4:7], v[80:83], v[12:15], v[4:7]
	v_mfma_f32_16x16x32_bf16 v[0:3], v[84:87], v[12:15], v[0:3]
	s_cbranch_vccnz .LBB0_373
	ds_read_b128 v[12:15], v172 offset:2304
	s_waitcnt lgkmcnt(0)
	v_lshlrev_b32_e32 v16, 16, v12
	v_and_b32_e32 v12, 0xffff0000, v12
	v_mul_f32_e32 v16, v39, v16
	v_mul_f32_e32 v12, v38, v12
	v_cvt_pk_bf16_f32 v12, v16, v12
	v_lshlrev_b32_e32 v16, 16, v13
	v_and_b32_e32 v13, 0xffff0000, v13
	v_mul_f32_e32 v16, v37, v16
	v_mul_f32_e32 v13, v36, v13
	v_cvt_pk_bf16_f32 v13, v16, v13
	v_lshlrev_b32_e32 v16, 16, v14
	v_and_b32_e32 v14, 0xffff0000, v14
	v_mul_f32_e32 v16, v32, v16
	v_mul_f32_e32 v14, v33, v14
	v_cvt_pk_bf16_f32 v14, v16, v14
	v_lshlrev_b32_e32 v16, 16, v15
	v_and_b32_e32 v15, 0xffff0000, v15
	v_mul_f32_e32 v15, v35, v15
	v_mul_f32_e32 v16, v34, v16
	v_cvt_pk_bf16_f32 v15, v16, v15
	s_nop 0
	v_mfma_f32_16x16x32_bf16 v[4:7], v[76:79], v[12:15], v[4:7]
	v_mfma_f32_16x16x32_bf16 v[0:3], v[72:75], v[12:15], v[0:3]

.LBB0_375:
	global_load_dword v14, v[168:169], off offset:192
	v_add_u32_e32 v12, s40, v242
	v_ashrrev_i32_e32 v13, 31, v12
	v_lshlrev_b32_e32 v15, 16, v11
	v_and_b32_e32 v11, 0xffff0000, v11
	v_lshlrev_b32_e32 v16, 16, v10
	v_lshlrev_b32_e32 v17, 16, v9
	v_and_b32_e32 v18, 0xffff0000, v9
	v_lshlrev_b32_e32 v19, 16, v8
	v_and_b32_e32 v20, 0xffff0000, v8
	v_lshlrev_b64 v[8:9], 12, v[12:13]
	v_and_b32_e32 v10, 0xffff0000, v10
	v_lshl_add_u64 v[8:9], s[12:13], 0, v[8:9]
	s_waitcnt vmcnt(0)
	v_fma_f32 v4, v116, v4, v14
	v_fma_f32 v5, v117, v5, v14
	v_fma_f32 v6, v118, v6, v14
	v_fma_f32 v7, v119, v7, v14
	v_fma_f32 v0, v112, v0, v14
	v_fma_f32 v1, v113, v1, v14
	v_fma_f32 v2, v114, v2, v14
	v_fmac_f32_e32 v14, v115, v3
	v_mul_f32_e32 v3, v4, v15
	v_mul_f32_e32 v4, v5, v11
	v_mul_f32_e32 v5, v6, v16
	v_mul_f32_e32 v6, v7, v10
	v_mul_f32_e32 v7, v0, v17
	v_mul_f32_e32 v10, v1, v18
	v_cvt_pk_bf16_f32 v0, v3, v4
	v_cvt_pk_bf16_f32 v1, v5, v6
	v_lshl_add_u64 v[4:5], v[228:229], 1, v[8:9]
	v_mul_f32_e32 v11, v2, v19
	v_mul_f32_e32 v12, v14, v20
	v_cvt_pk_bf16_f32 v2, v7, v10
	v_cvt_pk_bf16_f32 v3, v11, v12
	global_store_dwordx4 v[4:5], v[0:3], off sc1
	s_andn2_b64 vcc, exec, s[6:7]
	s_mov_b64 s[6:7], -1
	s_cbranch_vccnz .LBB0_298
